# hand-off version plus saddr-form LDS-DMA loads in the K-loops (no VALU address adds in the load phase)
# baseline (speedup 1.0000x reference)
; #define PG8_STAGE(bufoff, gbase, voff) do { _Pragma("unroll") for (int _i = 0; _i < 2; ++_i) \
;         __builtin_amdgcn_global_load_lds((const unsigned*)((const char*)(gbase) + (voff)[_i]), (LAS unsigned*)(lds + (bufoff) + ldsw + _i * 8192), 16, 0, 0); } while (0)
; #define PG8_LDA(dst, b, h) do { _Pragma("unroll") for (int m = 0; m < 4; ++m) _Pragma("unroll") for (int k = 0; k < 2; ++k) dst[m][k] = *(const LAS bf16x8*)(lds + PG8_SA(b, h) + aoff + m * 2048 + k * 1024); } while (0)
; #define PG8_LDB(dst, b, h) do { _Pragma("unroll") for (int n = 0; n < 2; ++n) _Pragma("unroll") for (int k = 0; k < 2; ++k) dst[n][k] = *(const LAS bf16x8*)(lds + PG8_SB(b, h) + boff + n * 2048 + k * 1024); } while (0)
; #define PG8_MMA(ai, bj, At, Bt) do { __builtin_amdgcn_s_setprio(1); _Pragma("unroll") for (int m = 0; m < 4; ++m) _Pragma("unroll") for (int n = 0; n < 2; ++n) _Pragma("unroll") for (int k = 0; k < 2; ++k) \
;         acc[ai][bj][m][n] = __builtin_amdgcn_mfma_f32_16x16x32_bf16(Bt[n][k], At[m][k], acc[ai][bj][m][n], 0, 0, 0); __builtin_amdgcn_s_setprio(0); } while (0)
; #define PG8_WAIT_V(n) asm volatile("s_waitcnt vmcnt(" #n ")" ::: "memory")
; #define PG8_WAIT_L(n) asm volatile("s_waitcnt lgkmcnt(" #n ")" ::: "memory")
; #define PG8_BAR __builtin_amdgcn_s_barrier()
; #define PG8_SCHED __builtin_amdgcn_sched_barrier(0)
; template <class Epi, class Sched>
; __device__ __forceinline__ void gemm_phase(LAS unsigned char* lds, const int K, const Sched& S, const Epi& E) {
;     ...
;             const bool last = (t == nt - 2);
;             const char* a1 = cA + (size_t)(t + 1) * kstep;
;             const char* a2 = last ? nA : cA + (size_t)(t + 2) * kstep; const char* b2 = last ? nB : cB + (size_t)(t + 2) * kstep;
;             const char* a3 = a2 + kstep; const char* b3 = b2 + kstep;
;             PG8_LDB(B0, 0, 0); PG8_LDB(B1, 0, 1); PG8_SCHED; PG8_LDA(At, 0, 0); PG8_STAGE(PG8_SA(1, 1), a1 + hstep, voffA);
;             PG8_WAIT_V(8); PG8_WAIT_L(0); PG8_BAR; PG8_MMA(0, 0, At, B0); PG8_MMA(0, 1, At, B1); PG8_BAR; PG8_SCHED;
;             PG8_LDA(At, 0, 1); PG8_STAGE(PG8_SB(0, 0), b2, voffB); PG8_STAGE(PG8_SB(0, 1), b2 + hstep, voffB); PG8_STAGE(PG8_SA(0, 0), a2, voffA);
;             PG8_WAIT_V(8); PG8_WAIT_L(0); PG8_BAR; PG8_MMA(1, 0, At, B0); PG8_MMA(1, 1, At, B1); PG8_BAR; PG8_SCHED;
.LBB0_403:
	s_add_u32 s14, s8, 0xfffc0080
	s_addc_u32 s15, s9, -1
	s_add_i32 s16, 0, 0x10000
	s_cmp_eq_u32 s13, 12
	s_cselect_b32 s55, s2, s15
	s_cselect_b32 s54, s4, s14
	v_add_u32_e32 v128, s16, v149
	s_cselect_b32 s39, s5, s12
	s_cselect_b32 s38, s10, s11
	s_add_i32 s17, 0, 0x14000
	ds_read_b128 v[158:161], v128
	ds_read_b128 v[162:165], v128 offset:1024
	ds_read_b128 v[184:187], v128 offset:2048
	ds_read_b128 v[188:191], v128 offset:3072
	v_add_u32_e32 v128, s17, v149
	ds_read_b128 v[192:195], v128
	ds_read_b128 v[196:199], v128 offset:1024
	ds_read_b128 v[200:203], v128 offset:2048
	ds_read_b128 v[204:207], v128 offset:3072
	s_add_i32 m0, s59, 0xc000
	ds_read_b128 v[208:211], v147
	ds_read_b128 v[212:215], v147 offset:1024
	ds_read_b128 v[216:219], v147 offset:2048
	ds_read_b128 v[220:223], v147 offset:3072
	ds_read_b128 v[224:227], v147 offset:4096
	ds_read_b128 v[228:231], v147 offset:5120
	ds_read_b128 v[232:235], v147 offset:6144
	ds_read_b128 v[236:239], v147 offset:7168
	global_load_lds_dwordx4 v154, s[8:9]
	s_add_i32 m0, s59, 0xe000
	s_nop 0
	global_load_lds_dwordx4 v156, s[8:9]
	s_waitcnt vmcnt(8)
	s_waitcnt lgkmcnt(0)
	s_setprio 1
	s_barrier
	v_mfma_f32_16x16x32_bf16 v[124:127], v[158:161], v[208:211], v[124:127]
	v_mfma_f32_16x16x32_bf16 v[120:123], v[184:187], v[208:211], v[120:123]
	v_mfma_f32_16x16x32_bf16 v[108:111], v[158:161], v[216:219], v[108:111]
	v_mfma_f32_16x16x32_bf16 v[104:107], v[184:187], v[216:219], v[104:107]
	v_mfma_f32_16x16x32_bf16 v[92:95], v[158:161], v[224:227], v[92:95]
	v_mfma_f32_16x16x32_bf16 v[88:91], v[184:187], v[224:227], v[88:91]
	v_mfma_f32_16x16x32_bf16 v[76:79], v[158:161], v[232:235], v[76:79]
	v_mfma_f32_16x16x32_bf16 v[72:75], v[184:187], v[232:235], v[72:75]
	v_mfma_f32_16x16x32_bf16 v[124:127], v[162:165], v[212:215], v[124:127]
	v_mfma_f32_16x16x32_bf16 v[120:123], v[188:191], v[212:215], v[120:123]
	v_mfma_f32_16x16x32_bf16 v[108:111], v[162:165], v[220:223], v[108:111]
	v_mfma_f32_16x16x32_bf16 v[104:107], v[188:191], v[220:223], v[104:107]
	v_mfma_f32_16x16x32_bf16 v[92:95], v[162:165], v[228:231], v[92:95]
	v_mfma_f32_16x16x32_bf16 v[88:91], v[188:191], v[228:231], v[88:91]
	v_mfma_f32_16x16x32_bf16 v[76:79], v[162:165], v[236:239], v[76:79]
	v_mfma_f32_16x16x32_bf16 v[72:75], v[188:191], v[236:239], v[72:75]
	s_setprio 0
	s_setprio 1
	v_mfma_f32_16x16x32_bf16 v[116:119], v[192:195], v[208:211], v[116:119]
	v_mfma_f32_16x16x32_bf16 v[112:115], v[200:203], v[208:211], v[112:115]
	v_mfma_f32_16x16x32_bf16 v[100:103], v[192:195], v[216:219], v[100:103]
	v_mfma_f32_16x16x32_bf16 v[96:99], v[200:203], v[216:219], v[96:99]
	v_mfma_f32_16x16x32_bf16 v[84:87], v[192:195], v[224:227], v[84:87]
	v_mfma_f32_16x16x32_bf16 v[80:83], v[200:203], v[224:227], v[80:83]
	v_mfma_f32_16x16x32_bf16 v[68:71], v[192:195], v[232:235], v[68:71]
	v_mfma_f32_16x16x32_bf16 v[64:67], v[200:203], v[232:235], v[64:67]
	v_mfma_f32_16x16x32_bf16 v[116:119], v[196:199], v[212:215], v[116:119]
	v_mfma_f32_16x16x32_bf16 v[112:115], v[204:207], v[212:215], v[112:115]
	v_mfma_f32_16x16x32_bf16 v[100:103], v[196:199], v[220:223], v[100:103]
	v_mfma_f32_16x16x32_bf16 v[96:99], v[204:207], v[220:223], v[96:99]
	v_mfma_f32_16x16x32_bf16 v[84:87], v[196:199], v[228:231], v[84:87]
	v_mfma_f32_16x16x32_bf16 v[80:83], v[204:207], v[228:231], v[80:83]
	v_mfma_f32_16x16x32_bf16 v[68:71], v[196:199], v[236:239], v[68:71]
	v_mfma_f32_16x16x32_bf16 v[64:67], v[204:207], v[236:239], v[64:67]
	s_barrier
	s_setprio 0
	s_add_i32 s14, s16, s58
	s_mov_b32 m0, s14
	ds_read_b128 v[208:211], v147 offset:16384
	ds_read_b128 v[212:215], v147 offset:17408
	ds_read_b128 v[216:219], v147 offset:18432
	ds_read_b128 v[220:223], v147 offset:19456
	ds_read_b128 v[224:227], v147 offset:20480
	ds_read_b128 v[228:231], v147 offset:21504
	ds_read_b128 v[232:235], v147 offset:22528
	ds_read_b128 v[236:239], v147 offset:23552
	global_load_lds_dwordx4 v140, s[38:39]
	s_add_i32 m0, s14, 0x2000
	s_add_u32 s14, s38, 0x40000
	s_addc_u32 s15, s39, 0
	s_add_i32 s16, s17, s58
	global_load_lds_dwordx4 v144, s[38:39]
	s_mov_b32 m0, s16
	s_nop 0
	global_load_lds_dwordx4 v140, s[14:15]
	s_add_i32 m0, s16, 0x2000
	s_nop 0
	global_load_lds_dwordx4 v144, s[14:15]
	s_mov_b32 m0, s59
	s_nop 0
	global_load_lds_dwordx4 v138, s[54:55]
	s_mov_b32 m0, s60
	s_nop 0
	global_load_lds_dwordx4 v142, s[54:55]
	s_waitcnt vmcnt(8)
	s_waitcnt lgkmcnt(0)
	s_setprio 1
	s_barrier
	v_mfma_f32_16x16x32_bf16 v[60:63], v[158:161], v[208:211], v[60:63]
	v_mfma_f32_16x16x32_bf16 v[56:59], v[184:187], v[208:211], v[56:59]
	v_mfma_f32_16x16x32_bf16 v[44:47], v[158:161], v[216:219], v[44:47]
	v_mfma_f32_16x16x32_bf16 v[40:43], v[184:187], v[216:219], v[40:43]
	v_mfma_f32_16x16x32_bf16 v[28:31], v[158:161], v[224:227], v[28:31]
	v_mfma_f32_16x16x32_bf16 v[24:27], v[184:187], v[224:227], v[24:27]
	v_mfma_f32_16x16x32_bf16 v[12:15], v[158:161], v[232:235], v[12:15]
	v_mfma_f32_16x16x32_bf16 v[8:11], v[184:187], v[232:235], v[8:11]
	v_mfma_f32_16x16x32_bf16 v[60:63], v[162:165], v[212:215], v[60:63]
	v_mfma_f32_16x16x32_bf16 v[56:59], v[188:191], v[212:215], v[56:59]
	v_mfma_f32_16x16x32_bf16 v[44:47], v[162:165], v[220:223], v[44:47]
	v_mfma_f32_16x16x32_bf16 v[40:43], v[188:191], v[220:223], v[40:43]
	v_mfma_f32_16x16x32_bf16 v[28:31], v[162:165], v[228:231], v[28:31]
	v_mfma_f32_16x16x32_bf16 v[24:27], v[188:191], v[228:231], v[24:27]
	v_mfma_f32_16x16x32_bf16 v[12:15], v[162:165], v[236:239], v[12:15]
	v_mfma_f32_16x16x32_bf16 v[8:11], v[188:191], v[236:239], v[8:11]
	s_setprio 0
	s_setprio 1
	v_mfma_f32_16x16x32_bf16 v[52:55], v[192:195], v[208:211], v[52:55]
	v_mfma_f32_16x16x32_bf16 v[48:51], v[200:203], v[208:211], v[48:51]
	v_mfma_f32_16x16x32_bf16 v[36:39], v[192:195], v[216:219], v[36:39]
	v_mfma_f32_16x16x32_bf16 v[32:35], v[200:203], v[216:219], v[32:35]
	v_mfma_f32_16x16x32_bf16 v[20:23], v[192:195], v[224:227], v[20:23]
	v_mfma_f32_16x16x32_bf16 v[16:19], v[200:203], v[224:227], v[16:19]
	v_mfma_f32_16x16x32_bf16 v[4:7], v[192:195], v[232:235], v[4:7]
	v_mfma_f32_16x16x32_bf16 v[0:3], v[200:203], v[232:235], v[0:3]
	v_mfma_f32_16x16x32_bf16 v[52:55], v[196:199], v[212:215], v[52:55]
	v_mfma_f32_16x16x32_bf16 v[48:51], v[204:207], v[212:215], v[48:51]
	v_mfma_f32_16x16x32_bf16 v[36:39], v[196:199], v[220:223], v[36:39]
	v_mfma_f32_16x16x32_bf16 v[32:35], v[204:207], v[220:223], v[32:35]
	v_mfma_f32_16x16x32_bf16 v[20:23], v[196:199], v[228:231], v[20:23]
	v_mfma_f32_16x16x32_bf16 v[16:19], v[204:207], v[228:231], v[16:19]
	v_mfma_f32_16x16x32_bf16 v[4:7], v[196:199], v[236:239], v[4:7]
	v_mfma_f32_16x16x32_bf16 v[0:3], v[204:207], v[236:239], v[0:3]
	s_barrier
; #define PG8_STAGE(bufoff, gbase, voff) do { _Pragma("unroll") for (int _i = 0; _i < 2; ++_i) \
;         __builtin_amdgcn_global_load_lds((const unsigned*)((const char*)(gbase) + (voff)[_i]), (LAS unsigned*)(lds + (bufoff) + ldsw + _i * 8192), 16, 0, 0); } while (0)
; #define PG8_LDA(dst, b, h) do { _Pragma("unroll") for (int m = 0; m < 4; ++m) _Pragma("unroll") for (int k = 0; k < 2; ++k) dst[m][k] = *(const LAS bf16x8*)(lds + PG8_SA(b, h) + aoff + m * 2048 + k * 1024); } while (0)
; #define PG8_LDB(dst, b, h) do { _Pragma("unroll") for (int n = 0; n < 2; ++n) _Pragma("unroll") for (int k = 0; k < 2; ++k) dst[n][k] = *(const LAS bf16x8*)(lds + PG8_SB(b, h) + boff + n * 2048 + k * 1024); } while (0)
; #define PG8_MMA(ai, bj, At, Bt) do { __builtin_amdgcn_s_setprio(1); _Pragma("unroll") for (int m = 0; m < 4; ++m) _Pragma("unroll") for (int n = 0; n < 2; ++n) _Pragma("unroll") for (int k = 0; k < 2; ++k) \
;         acc[ai][bj][m][n] = __builtin_amdgcn_mfma_f32_16x16x32_bf16(Bt[n][k], At[m][k], acc[ai][bj][m][n], 0, 0, 0); __builtin_amdgcn_s_setprio(0); } while (0)
; #define PG8_WAIT_V(n) asm volatile("s_waitcnt vmcnt(" #n ")" ::: "memory")
; #define PG8_WAIT_L(n) asm volatile("s_waitcnt lgkmcnt(" #n ")" ::: "memory")
; #define PG8_BAR __builtin_amdgcn_s_barrier()
; #define PG8_SCHED __builtin_amdgcn_sched_barrier(0)
; template <class Epi, class Sched>
; __device__ __forceinline__ void gemm_phase(LAS unsigned char* lds, const int K, const Sched& S, const Epi& E) {
;     ...
;             PG8_LDB(B0, 1, 0); PG8_LDB(B1, 1, 1); PG8_SCHED; PG8_LDA(At, 1, 0); PG8_STAGE(PG8_SA(0, 1), a2 + hstep, voffA);
;             PG8_WAIT_V(8); PG8_WAIT_L(0); PG8_BAR; PG8_MMA(0, 0, At, B0); PG8_MMA(0, 1, At, B1); PG8_BAR; PG8_SCHED;
;             PG8_LDA(At, 1, 1); PG8_STAGE(PG8_SB(1, 0), b3, voffB); PG8_STAGE(PG8_SB(1, 1), b3 + hstep, voffB); PG8_STAGE(PG8_SA(1, 0), a3, voffA);
;             PG8_WAIT_V(8); PG8_WAIT_L(0); PG8_BAR; PG8_MMA(1, 0, At, B0); PG8_MMA(1, 1, At, B1); PG8_BAR; PG8_SCHED;
;         }
;         if (wr == 0) PG8_BAR;
	s_setprio 0
	s_add_i32 s16, 0, 0x18000
	v_add_u32_e32 v128, s16, v149
	s_add_i32 s17, 0, 0x1c000
	ds_read_b128 v[158:161], v128
	ds_read_b128 v[162:165], v128 offset:1024
	ds_read_b128 v[184:187], v128 offset:2048
	ds_read_b128 v[188:191], v128 offset:3072
	v_add_u32_e32 v128, s17, v149
	ds_read_b128 v[192:195], v128
	ds_read_b128 v[196:199], v128 offset:1024
	ds_read_b128 v[200:203], v128 offset:2048
	ds_read_b128 v[204:207], v128 offset:3072
	s_add_u32 s14, s54, 0x40000
	s_addc_u32 s15, s55, 0
	s_mov_b32 m0, s61
	ds_read_b128 v[208:211], v147 offset:32768
	ds_read_b128 v[212:215], v147 offset:33792
	ds_read_b128 v[216:219], v147 offset:34816
	ds_read_b128 v[220:223], v147 offset:35840
	ds_read_b128 v[224:227], v147 offset:36864
	ds_read_b128 v[228:231], v147 offset:37888
	ds_read_b128 v[232:235], v147 offset:38912
	ds_read_b128 v[236:239], v147 offset:39936
	global_load_lds_dwordx4 v138, s[14:15]
	s_mov_b32 m0, s62
	s_nop 0
	global_load_lds_dwordx4 v142, s[14:15]
	s_waitcnt vmcnt(8)
	s_waitcnt lgkmcnt(0)
	s_setprio 1
	s_barrier
	v_mfma_f32_16x16x32_bf16 v[124:127], v[158:161], v[208:211], v[124:127]
	v_mfma_f32_16x16x32_bf16 v[120:123], v[184:187], v[208:211], v[120:123]
	v_mfma_f32_16x16x32_bf16 v[108:111], v[158:161], v[216:219], v[108:111]
	v_mfma_f32_16x16x32_bf16 v[104:107], v[184:187], v[216:219], v[104:107]
	v_mfma_f32_16x16x32_bf16 v[92:95], v[158:161], v[224:227], v[92:95]
	v_mfma_f32_16x16x32_bf16 v[88:91], v[184:187], v[224:227], v[88:91]
	v_mfma_f32_16x16x32_bf16 v[76:79], v[158:161], v[232:235], v[76:79]
	v_mfma_f32_16x16x32_bf16 v[72:75], v[184:187], v[232:235], v[72:75]
	v_mfma_f32_16x16x32_bf16 v[124:127], v[162:165], v[212:215], v[124:127]
	v_mfma_f32_16x16x32_bf16 v[120:123], v[188:191], v[212:215], v[120:123]
	v_mfma_f32_16x16x32_bf16 v[108:111], v[162:165], v[220:223], v[108:111]
	v_mfma_f32_16x16x32_bf16 v[104:107], v[188:191], v[220:223], v[104:107]
	v_mfma_f32_16x16x32_bf16 v[92:95], v[162:165], v[228:231], v[92:95]
	v_mfma_f32_16x16x32_bf16 v[88:91], v[188:191], v[228:231], v[88:91]
	v_mfma_f32_16x16x32_bf16 v[76:79], v[162:165], v[236:239], v[76:79]
	v_mfma_f32_16x16x32_bf16 v[72:75], v[188:191], v[236:239], v[72:75]
	s_setprio 0
	s_setprio 1
	v_mfma_f32_16x16x32_bf16 v[116:119], v[192:195], v[208:211], v[116:119]
	v_mfma_f32_16x16x32_bf16 v[112:115], v[200:203], v[208:211], v[112:115]
	v_mfma_f32_16x16x32_bf16 v[100:103], v[192:195], v[216:219], v[100:103]
	v_mfma_f32_16x16x32_bf16 v[96:99], v[200:203], v[216:219], v[96:99]
	v_mfma_f32_16x16x32_bf16 v[84:87], v[192:195], v[224:227], v[84:87]
	v_mfma_f32_16x16x32_bf16 v[80:83], v[200:203], v[224:227], v[80:83]
	v_mfma_f32_16x16x32_bf16 v[68:71], v[192:195], v[232:235], v[68:71]
	v_mfma_f32_16x16x32_bf16 v[64:67], v[200:203], v[232:235], v[64:67]
	v_mfma_f32_16x16x32_bf16 v[116:119], v[196:199], v[212:215], v[116:119]
	v_mfma_f32_16x16x32_bf16 v[112:115], v[204:207], v[212:215], v[112:115]
	v_mfma_f32_16x16x32_bf16 v[100:103], v[196:199], v[220:223], v[100:103]
	v_mfma_f32_16x16x32_bf16 v[96:99], v[204:207], v[220:223], v[96:99]
	v_mfma_f32_16x16x32_bf16 v[84:87], v[196:199], v[228:231], v[84:87]
	v_mfma_f32_16x16x32_bf16 v[80:83], v[204:207], v[228:231], v[80:83]
	v_mfma_f32_16x16x32_bf16 v[68:71], v[196:199], v[236:239], v[68:71]
	v_mfma_f32_16x16x32_bf16 v[64:67], v[204:207], v[236:239], v[64:67]
	s_barrier
	s_setprio 0
	s_add_i32 s14, s16, s58
	s_mov_b32 m0, s14
	ds_read_b128 v[208:211], v147 offset:49152
	ds_read_b128 v[212:215], v147 offset:50176
	ds_read_b128 v[216:219], v147 offset:51200
	ds_read_b128 v[220:223], v147 offset:52224
	ds_read_b128 v[224:227], v147 offset:53248
	ds_read_b128 v[228:231], v147 offset:54272
	ds_read_b128 v[232:235], v147 offset:55296
	ds_read_b128 v[236:239], v147 offset:56320
	s_add_u32 s100, s38, s36
	s_addc_u32 s101, s39, s37
	global_load_lds_dwordx4 v140, s[100:101]
	s_add_i32 m0, s14, 0x2000
	s_add_u32 s14, s38, 0x40080
	s_addc_u32 s15, s39, 0
	s_add_i32 s16, s17, s58
	s_add_u32 s100, s38, s36
	s_addc_u32 s101, s39, s37
	global_load_lds_dwordx4 v144, s[100:101]
	s_mov_b32 m0, s16
	s_nop 0
	global_load_lds_dwordx4 v140, s[14:15]
	s_add_i32 m0, s16, 0x2000
	s_nop 0
	global_load_lds_dwordx4 v144, s[14:15]
	s_mov_b32 m0, s64
	s_nop 0
	s_add_u32 s100, s54, s36
	s_addc_u32 s101, s55, s37
	global_load_lds_dwordx4 v138, s[100:101]
	s_mov_b32 m0, s65
	s_nop 0
	s_add_u32 s100, s54, s36
	s_addc_u32 s101, s55, s37
	global_load_lds_dwordx4 v142, s[100:101]
	s_waitcnt vmcnt(8)
	s_waitcnt lgkmcnt(0)
	s_setprio 1
	s_barrier
	v_mfma_f32_16x16x32_bf16 v[60:63], v[158:161], v[208:211], v[60:63]
	v_mfma_f32_16x16x32_bf16 v[56:59], v[184:187], v[208:211], v[56:59]
	v_mfma_f32_16x16x32_bf16 v[44:47], v[158:161], v[216:219], v[44:47]
	v_mfma_f32_16x16x32_bf16 v[40:43], v[184:187], v[216:219], v[40:43]
	v_mfma_f32_16x16x32_bf16 v[28:31], v[158:161], v[224:227], v[28:31]
	v_mfma_f32_16x16x32_bf16 v[24:27], v[184:187], v[224:227], v[24:27]
	v_mfma_f32_16x16x32_bf16 v[12:15], v[158:161], v[232:235], v[12:15]
	v_mfma_f32_16x16x32_bf16 v[8:11], v[184:187], v[232:235], v[8:11]
	v_mfma_f32_16x16x32_bf16 v[60:63], v[162:165], v[212:215], v[60:63]
	v_mfma_f32_16x16x32_bf16 v[56:59], v[188:191], v[212:215], v[56:59]
	v_mfma_f32_16x16x32_bf16 v[44:47], v[162:165], v[220:223], v[44:47]
	v_mfma_f32_16x16x32_bf16 v[40:43], v[188:191], v[220:223], v[40:43]
	v_mfma_f32_16x16x32_bf16 v[28:31], v[162:165], v[228:231], v[28:31]
	v_mfma_f32_16x16x32_bf16 v[24:27], v[188:191], v[228:231], v[24:27]
	v_mfma_f32_16x16x32_bf16 v[12:15], v[162:165], v[236:239], v[12:15]
	v_mfma_f32_16x16x32_bf16 v[8:11], v[188:191], v[236:239], v[8:11]
	s_setprio 0
	s_setprio 1
	v_mfma_f32_16x16x32_bf16 v[52:55], v[192:195], v[208:211], v[52:55]
	v_mfma_f32_16x16x32_bf16 v[48:51], v[200:203], v[208:211], v[48:51]
	v_mfma_f32_16x16x32_bf16 v[36:39], v[192:195], v[216:219], v[36:39]
	v_mfma_f32_16x16x32_bf16 v[32:35], v[200:203], v[216:219], v[32:35]
	v_mfma_f32_16x16x32_bf16 v[20:23], v[192:195], v[224:227], v[20:23]
	v_mfma_f32_16x16x32_bf16 v[16:19], v[200:203], v[224:227], v[16:19]
	v_mfma_f32_16x16x32_bf16 v[4:7], v[192:195], v[232:235], v[4:7]
	v_mfma_f32_16x16x32_bf16 v[0:3], v[200:203], v[232:235], v[0:3]
	v_mfma_f32_16x16x32_bf16 v[52:55], v[196:199], v[212:215], v[52:55]
	v_mfma_f32_16x16x32_bf16 v[48:51], v[204:207], v[212:215], v[48:51]
	v_mfma_f32_16x16x32_bf16 v[36:39], v[196:199], v[220:223], v[36:39]
	v_mfma_f32_16x16x32_bf16 v[32:35], v[204:207], v[220:223], v[32:35]
	v_mfma_f32_16x16x32_bf16 v[20:23], v[196:199], v[228:231], v[20:23]
	v_mfma_f32_16x16x32_bf16 v[16:19], v[204:207], v[228:231], v[16:19]
	v_mfma_f32_16x16x32_bf16 v[4:7], v[196:199], v[236:239], v[4:7]
	v_mfma_f32_16x16x32_bf16 v[0:3], v[204:207], v[236:239], v[0:3]
	s_barrier
	s_setprio 0
	s_add_i32 s13, s13, 2
	s_add_u32 s8, s8, 0x100
	s_addc_u32 s9, s9, 0
	s_add_u32 s11, s11, 0x100
	s_addc_u32 s12, s12, 0
	s_cmp_gt_u32 s13, 13
	s_cbranch_scc0 .LBB0_403
	s_and_b64 vcc, exec, s[42:43]
	s_cbranch_vccz .LBB0_406
	s_barrier

; #define PG8_STAGE(bufoff, gbase, voff) do { _Pragma("unroll") for (int _i = 0; _i < 2; ++_i) \
;         __builtin_amdgcn_global_load_lds((const unsigned*)((const char*)(gbase) + (voff)[_i]), (LAS unsigned*)(lds + (bufoff) + ldsw + _i * 8192), 16, 0, 0); } while (0)
; #define PG8_LDA(dst, b, h) do { _Pragma("unroll") for (int m = 0; m < 4; ++m) _Pragma("unroll") for (int k = 0; k < 2; ++k) dst[m][k] = *(const LAS bf16x8*)(lds + PG8_SA(b, h) + aoff + m * 2048 + k * 1024); } while (0)
; #define PG8_LDB(dst, b, h) do { _Pragma("unroll") for (int n = 0; n < 2; ++n) _Pragma("unroll") for (int k = 0; k < 2; ++k) dst[n][k] = *(const LAS bf16x8*)(lds + PG8_SB(b, h) + boff + n * 2048 + k * 1024); } while (0)
; #define PG8_MMA(ai, bj, At, Bt) do { __builtin_amdgcn_s_setprio(1); _Pragma("unroll") for (int m = 0; m < 4; ++m) _Pragma("unroll") for (int n = 0; n < 2; ++n) _Pragma("unroll") for (int k = 0; k < 2; ++k) \
;         acc[ai][bj][m][n] = __builtin_amdgcn_mfma_f32_16x16x32_bf16(Bt[n][k], At[m][k], acc[ai][bj][m][n], 0, 0, 0); __builtin_amdgcn_s_setprio(0); } while (0)
; #define PG8_WAIT_V(n) asm volatile("s_waitcnt vmcnt(" #n ")" ::: "memory")
; #define PG8_WAIT_L(n) asm volatile("s_waitcnt lgkmcnt(" #n ")" ::: "memory")
; #define PG8_BAR __builtin_amdgcn_s_barrier()
; #define PG8_SCHED __builtin_amdgcn_sched_barrier(0)
; template <class Epi, class Sched>
; __device__ __forceinline__ void gemm_phase(LAS unsigned char* lds, const int K, const Sched& S, const Epi& E) {
;     ...
;             const bool last = (t == nt - 2);
;             const char* a1 = cA + (size_t)(t + 1) * kstep;
;             const char* a2 = last ? nA : cA + (size_t)(t + 2) * kstep; const char* b2 = last ? nB : cB + (size_t)(t + 2) * kstep;
;             const char* a3 = a2 + kstep; const char* b3 = b2 + kstep;
;             PG8_LDB(B0, 0, 0); PG8_LDB(B1, 0, 1); PG8_SCHED; PG8_LDA(At, 0, 0); PG8_STAGE(PG8_SA(1, 1), a1 + hstep, voffA);
;             PG8_WAIT_V(8); PG8_WAIT_L(0); PG8_BAR; PG8_MMA(0, 0, At, B0); PG8_MMA(0, 1, At, B1); PG8_BAR; PG8_SCHED;
;             PG8_LDA(At, 0, 1); PG8_STAGE(PG8_SB(0, 0), b2, voffB); PG8_STAGE(PG8_SB(0, 1), b2 + hstep, voffB); PG8_STAGE(PG8_SA(0, 0), a2, voffA);
;             PG8_WAIT_V(8); PG8_WAIT_L(0); PG8_BAR; PG8_MMA(1, 0, At, B0); PG8_MMA(1, 1, At, B1); PG8_BAR; PG8_SCHED;
.LBB0_511:
	s_add_i32 s14, s8, 0xfaf9e080
	s_cmp_lg_u32 s13, 60
	s_cselect_b32 s14, s14, 0
	s_add_u32 s40, s28, s14
	s_addc_u32 s41, s29, 0
	s_add_i32 s15, 0, 0x10000
	s_add_u32 s38, s34, s14
	s_addc_u32 s39, s35, 0
	s_add_i32 s16, 0, 0x14000
	v_add_u32_e32 v164, s15, v145
	v_add_u32_e32 v180, s16, v145
	ds_read_b128 v[152:155], v164
	ds_read_b128 v[156:159], v164 offset:1024
	ds_read_b128 v[160:163], v164 offset:2048
	ds_read_b128 v[164:167], v164 offset:3072
	ds_read_b128 v[184:187], v180
	ds_read_b128 v[188:191], v180 offset:1024
	ds_read_b128 v[192:195], v180 offset:2048
	ds_read_b128 v[196:199], v180 offset:3072
	v_lshl_add_u64 v[180:181], v[146:147], 0, s[8:9]
	s_add_i32 m0, s2, 0xc000
	ds_read_b128 v[200:203], v151
	ds_read_b128 v[204:207], v151 offset:1024
	ds_read_b128 v[208:211], v151 offset:2048
	ds_read_b128 v[212:215], v151 offset:3072
	ds_read_b128 v[216:219], v151 offset:4096
	ds_read_b128 v[220:223], v151 offset:5120
	ds_read_b128 v[224:227], v151 offset:6144
	ds_read_b128 v[228:231], v151 offset:7168
	global_load_lds_dwordx4 v[180:181], off
	v_lshl_add_u64 v[180:181], v[148:149], 0, s[8:9]
	s_add_i32 m0, s2, 0xe000
	s_nop 0
	global_load_lds_dwordx4 v[180:181], off
	s_waitcnt vmcnt(8)
	s_waitcnt lgkmcnt(0)
	s_setprio 1
	s_barrier
	v_mfma_f32_16x16x32_bf16 v[124:127], v[152:155], v[200:203], v[124:127]
	v_mfma_f32_16x16x32_bf16 v[120:123], v[160:163], v[200:203], v[120:123]
	v_mfma_f32_16x16x32_bf16 v[108:111], v[152:155], v[208:211], v[108:111]
	v_mfma_f32_16x16x32_bf16 v[104:107], v[160:163], v[208:211], v[104:107]
	v_mfma_f32_16x16x32_bf16 v[92:95], v[152:155], v[216:219], v[92:95]
	v_mfma_f32_16x16x32_bf16 v[88:91], v[160:163], v[216:219], v[88:91]
	v_mfma_f32_16x16x32_bf16 v[76:79], v[152:155], v[224:227], v[76:79]
	v_mfma_f32_16x16x32_bf16 v[72:75], v[160:163], v[224:227], v[72:75]
	v_mfma_f32_16x16x32_bf16 v[124:127], v[156:159], v[204:207], v[124:127]
	v_mfma_f32_16x16x32_bf16 v[120:123], v[164:167], v[204:207], v[120:123]
	v_mfma_f32_16x16x32_bf16 v[108:111], v[156:159], v[212:215], v[108:111]
	v_mfma_f32_16x16x32_bf16 v[104:107], v[164:167], v[212:215], v[104:107]
	v_mfma_f32_16x16x32_bf16 v[92:95], v[156:159], v[220:223], v[92:95]
	v_mfma_f32_16x16x32_bf16 v[88:91], v[164:167], v[220:223], v[88:91]
	v_mfma_f32_16x16x32_bf16 v[76:79], v[156:159], v[228:231], v[76:79]
	v_mfma_f32_16x16x32_bf16 v[72:75], v[164:167], v[228:231], v[72:75]
	s_setprio 0
	s_setprio 1
	v_mfma_f32_16x16x32_bf16 v[116:119], v[184:187], v[200:203], v[116:119]
	v_mfma_f32_16x16x32_bf16 v[112:115], v[192:195], v[200:203], v[112:115]
	v_mfma_f32_16x16x32_bf16 v[100:103], v[184:187], v[208:211], v[100:103]
	v_mfma_f32_16x16x32_bf16 v[96:99], v[192:195], v[208:211], v[96:99]
	v_mfma_f32_16x16x32_bf16 v[84:87], v[184:187], v[216:219], v[84:87]
	v_mfma_f32_16x16x32_bf16 v[80:83], v[192:195], v[216:219], v[80:83]
	v_mfma_f32_16x16x32_bf16 v[68:71], v[184:187], v[224:227], v[68:71]
	v_mfma_f32_16x16x32_bf16 v[64:67], v[192:195], v[224:227], v[64:67]
	v_mfma_f32_16x16x32_bf16 v[116:119], v[188:191], v[204:207], v[116:119]
	v_mfma_f32_16x16x32_bf16 v[112:115], v[196:199], v[204:207], v[112:115]
	v_mfma_f32_16x16x32_bf16 v[100:103], v[188:191], v[212:215], v[100:103]
	v_mfma_f32_16x16x32_bf16 v[96:99], v[196:199], v[212:215], v[96:99]
	v_mfma_f32_16x16x32_bf16 v[84:87], v[188:191], v[220:223], v[84:87]
	v_mfma_f32_16x16x32_bf16 v[80:83], v[196:199], v[220:223], v[80:83]
	v_mfma_f32_16x16x32_bf16 v[68:71], v[188:191], v[228:231], v[68:71]
	v_mfma_f32_16x16x32_bf16 v[64:67], v[196:199], v[228:231], v[64:67]
	s_barrier
	s_setprio 0
	s_add_i32 s14, s15, s1
	s_mov_b32 m0, s14
	ds_read_b128 v[200:203], v151 offset:16384
	ds_read_b128 v[204:207], v151 offset:17408
	ds_read_b128 v[208:211], v151 offset:18432
	ds_read_b128 v[212:215], v151 offset:19456
	ds_read_b128 v[216:219], v151 offset:20480
	ds_read_b128 v[220:223], v151 offset:21504
	ds_read_b128 v[224:227], v151 offset:22528
	ds_read_b128 v[228:231], v151 offset:23552
	global_load_lds_dwordx4 v128, s[38:39]
	s_add_i32 m0, s14, 0x2000
	s_add_u32 s14, s38, 0x100000
	s_addc_u32 s15, s39, 0
	s_add_i32 s16, s16, s1
	global_load_lds_dwordx4 v138, s[38:39]
	s_mov_b32 m0, s16
	s_nop 0
	global_load_lds_dwordx4 v128, s[14:15]
	s_add_i32 m0, s16, 0x2000
	s_nop 0
	global_load_lds_dwordx4 v138, s[14:15]
	s_mov_b32 m0, s2
	s_nop 0
	global_load_lds_dwordx4 v142, s[40:41]
	s_mov_b32 m0, s3
	s_nop 0
	global_load_lds_dwordx4 v140, s[40:41]
	s_waitcnt vmcnt(8)
	s_waitcnt lgkmcnt(0)
	s_setprio 1
	s_barrier
	v_mfma_f32_16x16x32_bf16 v[60:63], v[152:155], v[200:203], v[60:63]
	v_mfma_f32_16x16x32_bf16 v[56:59], v[160:163], v[200:203], v[56:59]
	v_mfma_f32_16x16x32_bf16 v[44:47], v[152:155], v[208:211], v[44:47]
	v_mfma_f32_16x16x32_bf16 v[40:43], v[160:163], v[208:211], v[40:43]
	v_mfma_f32_16x16x32_bf16 v[28:31], v[152:155], v[216:219], v[28:31]
	v_mfma_f32_16x16x32_bf16 v[24:27], v[160:163], v[216:219], v[24:27]
	v_mfma_f32_16x16x32_bf16 v[12:15], v[152:155], v[224:227], v[12:15]
	v_mfma_f32_16x16x32_bf16 v[8:11], v[160:163], v[224:227], v[8:11]
	v_mfma_f32_16x16x32_bf16 v[60:63], v[156:159], v[204:207], v[60:63]
	v_mfma_f32_16x16x32_bf16 v[56:59], v[164:167], v[204:207], v[56:59]
	v_mfma_f32_16x16x32_bf16 v[44:47], v[156:159], v[212:215], v[44:47]
	v_mfma_f32_16x16x32_bf16 v[40:43], v[164:167], v[212:215], v[40:43]
	v_mfma_f32_16x16x32_bf16 v[28:31], v[156:159], v[220:223], v[28:31]
	v_mfma_f32_16x16x32_bf16 v[24:27], v[164:167], v[220:223], v[24:27]
	v_mfma_f32_16x16x32_bf16 v[12:15], v[156:159], v[228:231], v[12:15]
	v_mfma_f32_16x16x32_bf16 v[8:11], v[164:167], v[228:231], v[8:11]
	s_setprio 0
	s_setprio 1
	v_mfma_f32_16x16x32_bf16 v[52:55], v[184:187], v[200:203], v[52:55]
	v_mfma_f32_16x16x32_bf16 v[48:51], v[192:195], v[200:203], v[48:51]
	v_mfma_f32_16x16x32_bf16 v[36:39], v[184:187], v[208:211], v[36:39]
	v_mfma_f32_16x16x32_bf16 v[32:35], v[192:195], v[208:211], v[32:35]
	v_mfma_f32_16x16x32_bf16 v[20:23], v[184:187], v[216:219], v[20:23]
	v_mfma_f32_16x16x32_bf16 v[16:19], v[192:195], v[216:219], v[16:19]
	v_mfma_f32_16x16x32_bf16 v[4:7], v[184:187], v[224:227], v[4:7]
	v_mfma_f32_16x16x32_bf16 v[0:3], v[192:195], v[224:227], v[0:3]
	v_mfma_f32_16x16x32_bf16 v[52:55], v[188:191], v[204:207], v[52:55]
	v_mfma_f32_16x16x32_bf16 v[48:51], v[196:199], v[204:207], v[48:51]
	v_mfma_f32_16x16x32_bf16 v[36:39], v[188:191], v[212:215], v[36:39]
	v_mfma_f32_16x16x32_bf16 v[32:35], v[196:199], v[212:215], v[32:35]
	v_mfma_f32_16x16x32_bf16 v[20:23], v[188:191], v[220:223], v[20:23]
	v_mfma_f32_16x16x32_bf16 v[16:19], v[196:199], v[220:223], v[16:19]
	v_mfma_f32_16x16x32_bf16 v[4:7], v[188:191], v[228:231], v[4:7]
	v_mfma_f32_16x16x32_bf16 v[0:3], v[196:199], v[228:231], v[0:3]
	s_barrier
; #define PG8_STAGE(bufoff, gbase, voff) do { _Pragma("unroll") for (int _i = 0; _i < 2; ++_i) \
;         __builtin_amdgcn_global_load_lds((const unsigned*)((const char*)(gbase) + (voff)[_i]), (LAS unsigned*)(lds + (bufoff) + ldsw + _i * 8192), 16, 0, 0); } while (0)
; #define PG8_LDA(dst, b, h) do { _Pragma("unroll") for (int m = 0; m < 4; ++m) _Pragma("unroll") for (int k = 0; k < 2; ++k) dst[m][k] = *(const LAS bf16x8*)(lds + PG8_SA(b, h) + aoff + m * 2048 + k * 1024); } while (0)
; #define PG8_LDB(dst, b, h) do { _Pragma("unroll") for (int n = 0; n < 2; ++n) _Pragma("unroll") for (int k = 0; k < 2; ++k) dst[n][k] = *(const LAS bf16x8*)(lds + PG8_SB(b, h) + boff + n * 2048 + k * 1024); } while (0)
; #define PG8_MMA(ai, bj, At, Bt) do { __builtin_amdgcn_s_setprio(1); _Pragma("unroll") for (int m = 0; m < 4; ++m) _Pragma("unroll") for (int n = 0; n < 2; ++n) _Pragma("unroll") for (int k = 0; k < 2; ++k) \
;         acc[ai][bj][m][n] = __builtin_amdgcn_mfma_f32_16x16x32_bf16(Bt[n][k], At[m][k], acc[ai][bj][m][n], 0, 0, 0); __builtin_amdgcn_s_setprio(0); } while (0)
; #define PG8_WAIT_V(n) asm volatile("s_waitcnt vmcnt(" #n ")" ::: "memory")
; #define PG8_WAIT_L(n) asm volatile("s_waitcnt lgkmcnt(" #n ")" ::: "memory")
; #define PG8_BAR __builtin_amdgcn_s_barrier()
; #define PG8_SCHED __builtin_amdgcn_sched_barrier(0)
; template <class Epi, class Sched>
; __device__ __forceinline__ void gemm_phase(LAS unsigned char* lds, const int K, const Sched& S, const Epi& E) {
;     ...
;             PG8_LDB(B0, 1, 0); PG8_LDB(B1, 1, 1); PG8_SCHED; PG8_LDA(At, 1, 0); PG8_STAGE(PG8_SA(0, 1), a2 + hstep, voffA);
;             PG8_WAIT_V(8); PG8_WAIT_L(0); PG8_BAR; PG8_MMA(0, 0, At, B0); PG8_MMA(0, 1, At, B1); PG8_BAR; PG8_SCHED;
;             PG8_LDA(At, 1, 1); PG8_STAGE(PG8_SB(1, 0), b3, voffB); PG8_STAGE(PG8_SB(1, 1), b3 + hstep, voffB); PG8_STAGE(PG8_SA(1, 0), a3, voffA);
;             PG8_WAIT_V(8); PG8_WAIT_L(0); PG8_BAR; PG8_MMA(1, 0, At, B0); PG8_MMA(1, 1, At, B1); PG8_BAR; PG8_SCHED;
;         }
;         if (wr == 0) PG8_BAR;
	s_setprio 0
	s_add_i32 s16, 0, 0x18000
	s_add_i32 s17, 0, 0x1c000
	v_add_u32_e32 v164, s16, v145
	v_add_u32_e32 v196, s17, v145
	ds_read_b128 v[152:155], v164
	ds_read_b128 v[156:159], v164 offset:1024
	ds_read_b128 v[160:163], v164 offset:2048
	ds_read_b128 v[164:167], v164 offset:3072
	ds_read_b128 v[184:187], v196
	ds_read_b128 v[188:191], v196 offset:1024
	ds_read_b128 v[192:195], v196 offset:2048
	ds_read_b128 v[196:199], v196 offset:3072
	s_add_u32 s14, s40, 0x100000
	s_addc_u32 s15, s41, 0
	s_mov_b32 m0, s4
	ds_read_b128 v[200:203], v151 offset:32768
	ds_read_b128 v[204:207], v151 offset:33792
	ds_read_b128 v[208:211], v151 offset:34816
	ds_read_b128 v[212:215], v151 offset:35840
	ds_read_b128 v[216:219], v151 offset:36864
	ds_read_b128 v[220:223], v151 offset:37888
	ds_read_b128 v[224:227], v151 offset:38912
	ds_read_b128 v[228:231], v151 offset:39936
	global_load_lds_dwordx4 v142, s[14:15]
	s_mov_b32 m0, s5
	s_nop 0
	global_load_lds_dwordx4 v140, s[14:15]
	s_waitcnt vmcnt(8)
	s_waitcnt lgkmcnt(0)
	s_setprio 1
	s_barrier
	v_mfma_f32_16x16x32_bf16 v[124:127], v[152:155], v[200:203], v[124:127]
	v_mfma_f32_16x16x32_bf16 v[120:123], v[160:163], v[200:203], v[120:123]
	v_mfma_f32_16x16x32_bf16 v[108:111], v[152:155], v[208:211], v[108:111]
	v_mfma_f32_16x16x32_bf16 v[104:107], v[160:163], v[208:211], v[104:107]
	v_mfma_f32_16x16x32_bf16 v[92:95], v[152:155], v[216:219], v[92:95]
	v_mfma_f32_16x16x32_bf16 v[88:91], v[160:163], v[216:219], v[88:91]
	v_mfma_f32_16x16x32_bf16 v[76:79], v[152:155], v[224:227], v[76:79]
	v_mfma_f32_16x16x32_bf16 v[72:75], v[160:163], v[224:227], v[72:75]
	v_mfma_f32_16x16x32_bf16 v[124:127], v[156:159], v[204:207], v[124:127]
	v_mfma_f32_16x16x32_bf16 v[120:123], v[164:167], v[204:207], v[120:123]
	v_mfma_f32_16x16x32_bf16 v[108:111], v[156:159], v[212:215], v[108:111]
	v_mfma_f32_16x16x32_bf16 v[104:107], v[164:167], v[212:215], v[104:107]
	v_mfma_f32_16x16x32_bf16 v[92:95], v[156:159], v[220:223], v[92:95]
	v_mfma_f32_16x16x32_bf16 v[88:91], v[164:167], v[220:223], v[88:91]
	v_mfma_f32_16x16x32_bf16 v[76:79], v[156:159], v[228:231], v[76:79]
	v_mfma_f32_16x16x32_bf16 v[72:75], v[164:167], v[228:231], v[72:75]
	s_setprio 0
	s_setprio 1
	v_mfma_f32_16x16x32_bf16 v[116:119], v[184:187], v[200:203], v[116:119]
	v_mfma_f32_16x16x32_bf16 v[112:115], v[192:195], v[200:203], v[112:115]
	v_mfma_f32_16x16x32_bf16 v[100:103], v[184:187], v[208:211], v[100:103]
	v_mfma_f32_16x16x32_bf16 v[96:99], v[192:195], v[208:211], v[96:99]
	v_mfma_f32_16x16x32_bf16 v[84:87], v[184:187], v[216:219], v[84:87]
	v_mfma_f32_16x16x32_bf16 v[80:83], v[192:195], v[216:219], v[80:83]
	v_mfma_f32_16x16x32_bf16 v[68:71], v[184:187], v[224:227], v[68:71]
	v_mfma_f32_16x16x32_bf16 v[64:67], v[192:195], v[224:227], v[64:67]
	v_mfma_f32_16x16x32_bf16 v[116:119], v[188:191], v[204:207], v[116:119]
	v_mfma_f32_16x16x32_bf16 v[112:115], v[196:199], v[204:207], v[112:115]
	v_mfma_f32_16x16x32_bf16 v[100:103], v[188:191], v[212:215], v[100:103]
	v_mfma_f32_16x16x32_bf16 v[96:99], v[196:199], v[212:215], v[96:99]
	v_mfma_f32_16x16x32_bf16 v[84:87], v[188:191], v[220:223], v[84:87]
	v_mfma_f32_16x16x32_bf16 v[80:83], v[196:199], v[220:223], v[80:83]
	v_mfma_f32_16x16x32_bf16 v[68:71], v[188:191], v[228:231], v[68:71]
	v_mfma_f32_16x16x32_bf16 v[64:67], v[196:199], v[228:231], v[64:67]
	s_barrier
	s_setprio 0
	s_add_i32 s14, s16, s1
	s_mov_b32 m0, s14
	ds_read_b128 v[200:203], v151 offset:49152
	ds_read_b128 v[204:207], v151 offset:50176
	ds_read_b128 v[208:211], v151 offset:51200
	ds_read_b128 v[212:215], v151 offset:52224
	ds_read_b128 v[216:219], v151 offset:53248
	ds_read_b128 v[220:223], v151 offset:54272
	ds_read_b128 v[224:227], v151 offset:55296
	ds_read_b128 v[228:231], v151 offset:56320
	s_add_u32 s100, s38, s36
	s_addc_u32 s101, s39, s37
	global_load_lds_dwordx4 v128, s[100:101]
	s_add_i32 m0, s14, 0x2000
	s_add_u32 s14, s38, 0x100080
	s_addc_u32 s15, s39, 0
	s_add_i32 s16, s17, s1
	s_add_u32 s100, s38, s36
	s_addc_u32 s101, s39, s37
	global_load_lds_dwordx4 v138, s[100:101]
	s_mov_b32 m0, s16
	s_nop 0
	global_load_lds_dwordx4 v128, s[14:15]
	s_add_i32 m0, s16, 0x2000
	s_nop 0
	global_load_lds_dwordx4 v138, s[14:15]
	s_mov_b32 m0, s11
	s_nop 0
	s_add_u32 s100, s40, s36
	s_addc_u32 s101, s41, s37
	global_load_lds_dwordx4 v142, s[100:101]
	s_mov_b32 m0, s12
	s_nop 0
	s_add_u32 s100, s40, s36
	s_addc_u32 s101, s41, s37
	global_load_lds_dwordx4 v140, s[100:101]
	s_waitcnt vmcnt(8)
	s_waitcnt lgkmcnt(0)
	s_setprio 1
	s_barrier
	v_mfma_f32_16x16x32_bf16 v[60:63], v[152:155], v[200:203], v[60:63]
	v_mfma_f32_16x16x32_bf16 v[56:59], v[160:163], v[200:203], v[56:59]
	v_mfma_f32_16x16x32_bf16 v[44:47], v[152:155], v[208:211], v[44:47]
	v_mfma_f32_16x16x32_bf16 v[40:43], v[160:163], v[208:211], v[40:43]
	v_mfma_f32_16x16x32_bf16 v[28:31], v[152:155], v[216:219], v[28:31]
	v_mfma_f32_16x16x32_bf16 v[24:27], v[160:163], v[216:219], v[24:27]
	v_mfma_f32_16x16x32_bf16 v[12:15], v[152:155], v[224:227], v[12:15]
	v_mfma_f32_16x16x32_bf16 v[8:11], v[160:163], v[224:227], v[8:11]
	v_mfma_f32_16x16x32_bf16 v[60:63], v[156:159], v[204:207], v[60:63]
	v_mfma_f32_16x16x32_bf16 v[56:59], v[164:167], v[204:207], v[56:59]
	v_mfma_f32_16x16x32_bf16 v[44:47], v[156:159], v[212:215], v[44:47]
	v_mfma_f32_16x16x32_bf16 v[40:43], v[164:167], v[212:215], v[40:43]
	v_mfma_f32_16x16x32_bf16 v[28:31], v[156:159], v[220:223], v[28:31]
	v_mfma_f32_16x16x32_bf16 v[24:27], v[164:167], v[220:223], v[24:27]
	v_mfma_f32_16x16x32_bf16 v[12:15], v[156:159], v[228:231], v[12:15]
	v_mfma_f32_16x16x32_bf16 v[8:11], v[164:167], v[228:231], v[8:11]
	s_setprio 0
	s_setprio 1
	v_mfma_f32_16x16x32_bf16 v[52:55], v[184:187], v[200:203], v[52:55]
	v_mfma_f32_16x16x32_bf16 v[48:51], v[192:195], v[200:203], v[48:51]
	v_mfma_f32_16x16x32_bf16 v[36:39], v[184:187], v[208:211], v[36:39]
	v_mfma_f32_16x16x32_bf16 v[32:35], v[192:195], v[208:211], v[32:35]
	v_mfma_f32_16x16x32_bf16 v[20:23], v[184:187], v[216:219], v[20:23]
	v_mfma_f32_16x16x32_bf16 v[16:19], v[192:195], v[216:219], v[16:19]
	v_mfma_f32_16x16x32_bf16 v[4:7], v[184:187], v[224:227], v[4:7]
	v_mfma_f32_16x16x32_bf16 v[0:3], v[192:195], v[224:227], v[0:3]
	v_mfma_f32_16x16x32_bf16 v[52:55], v[188:191], v[204:207], v[52:55]
	v_mfma_f32_16x16x32_bf16 v[48:51], v[196:199], v[204:207], v[48:51]
	v_mfma_f32_16x16x32_bf16 v[36:39], v[188:191], v[212:215], v[36:39]
	v_mfma_f32_16x16x32_bf16 v[32:35], v[196:199], v[212:215], v[32:35]
	v_mfma_f32_16x16x32_bf16 v[20:23], v[188:191], v[220:223], v[20:23]
	v_mfma_f32_16x16x32_bf16 v[16:19], v[196:199], v[220:223], v[16:19]
	v_mfma_f32_16x16x32_bf16 v[4:7], v[188:191], v[228:231], v[4:7]
	v_mfma_f32_16x16x32_bf16 v[0:3], v[196:199], v[228:231], v[0:3]
	s_barrier
	s_setprio 0
	s_add_i32 s13, s13, 2
	s_add_u32 s8, s8, 0x100
	s_addc_u32 s9, s9, 0
	s_cmp_gt_u32 s13, 61
	s_cbranch_scc0 .LBB0_511
	s_cmpk_lt_u32 s0, 0x100
	s_cbranch_scc0 .LBB0_514
	s_barrier

; #define PG8_STAGE(bufoff, gbase, voff) do { _Pragma("unroll") for (int _i = 0; _i < 2; ++_i) \
;         __builtin_amdgcn_global_load_lds((const unsigned*)((const char*)(gbase) + (voff)[_i]), (LAS unsigned*)(lds + (bufoff) + ldsw + _i * 8192), 16, 0, 0); } while (0)
; #define PG8_LDA(dst, b, h) do { _Pragma("unroll") for (int m = 0; m < 4; ++m) _Pragma("unroll") for (int k = 0; k < 2; ++k) dst[m][k] = *(const LAS bf16x8*)(lds + PG8_SA(b, h) + aoff + m * 2048 + k * 1024); } while (0)
; #define PG8_LDB(dst, b, h) do { _Pragma("unroll") for (int n = 0; n < 2; ++n) _Pragma("unroll") for (int k = 0; k < 2; ++k) dst[n][k] = *(const LAS bf16x8*)(lds + PG8_SB(b, h) + boff + n * 2048 + k * 1024); } while (0)
; #define PG8_MMA(ai, bj, At, Bt) do { __builtin_amdgcn_s_setprio(1); _Pragma("unroll") for (int m = 0; m < 4; ++m) _Pragma("unroll") for (int n = 0; n < 2; ++n) _Pragma("unroll") for (int k = 0; k < 2; ++k) \
;         acc[ai][bj][m][n] = __builtin_amdgcn_mfma_f32_16x16x32_bf16(Bt[n][k], At[m][k], acc[ai][bj][m][n], 0, 0, 0); __builtin_amdgcn_s_setprio(0); } while (0)
; #define PG8_WAIT_V(n) asm volatile("s_waitcnt vmcnt(" #n ")" ::: "memory")
; #define PG8_WAIT_L(n) asm volatile("s_waitcnt lgkmcnt(" #n ")" ::: "memory")
; #define PG8_BAR __builtin_amdgcn_s_barrier()
; #define PG8_SCHED __builtin_amdgcn_sched_barrier(0)
; template <class Epi, class Sched>
; __device__ __forceinline__ void gemm_phase(LAS unsigned char* lds, const int K, const Sched& S, const Epi& E) {
;     ...
;             const bool last = (t == nt - 2);
;             const char* a1 = cA + (size_t)(t + 1) * kstep;
;             const char* a2 = last ? nA : cA + (size_t)(t + 2) * kstep; const char* b2 = last ? nB : cB + (size_t)(t + 2) * kstep;
;             const char* a3 = a2 + kstep; const char* b3 = b2 + kstep;
;             PG8_LDB(B0, 0, 0); PG8_LDB(B1, 0, 1); PG8_SCHED; PG8_LDA(At, 0, 0); PG8_STAGE(PG8_SA(1, 1), a1 + hstep, voffA);
;             PG8_WAIT_V(8); PG8_WAIT_L(0); PG8_BAR; PG8_MMA(0, 0, At, B0); PG8_MMA(0, 1, At, B1); PG8_BAR; PG8_SCHED;
;             PG8_LDA(At, 0, 1); PG8_STAGE(PG8_SB(0, 0), b2, voffB); PG8_STAGE(PG8_SB(0, 1), b2 + hstep, voffB); PG8_STAGE(PG8_SA(0, 0), a2, voffA);
;             PG8_WAIT_V(8); PG8_WAIT_L(0); PG8_BAR; PG8_MMA(1, 0, At, B0); PG8_MMA(1, 1, At, B1); PG8_BAR; PG8_SCHED;
.LBB0_812:
	s_add_i32 s16, s15, 2
	s_add_u32 s50, s8, 0x100
	s_addc_u32 s51, s9, 0
	s_add_i32 s17, 0, 0x10000
	s_cmp_eq_u32 s12, s15
	s_cselect_b32 s55, s4, s51
	s_cselect_b32 s54, s5, s50
	s_cselect_b32 s53, s10, s14
	s_cselect_b32 s52, s11, s13
	s_add_i32 s15, 0, 0x14000
	v_add_u32_e32 v158, s17, v164
	v_add_u32_e32 v162, s15, v164
	ds_read_b128 v[146:149], v158
	ds_read_b128 v[150:153], v158 offset:1024
	ds_read_b128 v[154:157], v158 offset:2048
	ds_read_b128 v[158:161], v158 offset:3072
	ds_read_b128 v[184:187], v162
	ds_read_b128 v[188:191], v162 offset:1024
	ds_read_b128 v[192:195], v162 offset:2048
	ds_read_b128 v[196:199], v162 offset:3072
	v_lshl_add_u64 v[162:163], s[8:9], 0, v[142:143]
	s_add_i32 m0, s26, 0xc000
	ds_read_b128 v[200:203], v166
	ds_read_b128 v[204:207], v166 offset:1024
	ds_read_b128 v[208:211], v166 offset:2048
	ds_read_b128 v[212:215], v166 offset:3072
	ds_read_b128 v[216:219], v166 offset:4096
	ds_read_b128 v[220:223], v166 offset:5120
	ds_read_b128 v[224:227], v166 offset:6144
	ds_read_b128 v[228:231], v166 offset:7168
	global_load_lds_dwordx4 v[162:163], off
	v_lshl_add_u64 v[162:163], s[8:9], 0, v[144:145]
	s_add_i32 m0, s26, 0xe000
	s_nop 0
	global_load_lds_dwordx4 v[162:163], off
	s_waitcnt vmcnt(8)
	s_waitcnt lgkmcnt(0)
	s_setprio 1
	s_barrier
	v_mfma_f32_16x16x32_bf16 v[124:127], v[146:149], v[200:203], v[124:127]
	v_mfma_f32_16x16x32_bf16 v[92:95], v[154:157], v[200:203], v[92:95]
	v_mfma_f32_16x16x32_bf16 v[120:123], v[146:149], v[208:211], v[120:123]
	v_mfma_f32_16x16x32_bf16 v[88:91], v[154:157], v[208:211], v[88:91]
	v_mfma_f32_16x16x32_bf16 v[116:119], v[146:149], v[216:219], v[116:119]
	v_mfma_f32_16x16x32_bf16 v[84:87], v[154:157], v[216:219], v[84:87]
	v_mfma_f32_16x16x32_bf16 v[112:115], v[146:149], v[224:227], v[112:115]
	v_mfma_f32_16x16x32_bf16 v[80:83], v[154:157], v[224:227], v[80:83]
	v_mfma_f32_16x16x32_bf16 v[124:127], v[150:153], v[204:207], v[124:127]
	v_mfma_f32_16x16x32_bf16 v[92:95], v[158:161], v[204:207], v[92:95]
	v_mfma_f32_16x16x32_bf16 v[120:123], v[150:153], v[212:215], v[120:123]
	v_mfma_f32_16x16x32_bf16 v[88:91], v[158:161], v[212:215], v[88:91]
	v_mfma_f32_16x16x32_bf16 v[116:119], v[150:153], v[220:223], v[116:119]
	v_mfma_f32_16x16x32_bf16 v[84:87], v[158:161], v[220:223], v[84:87]
	v_mfma_f32_16x16x32_bf16 v[112:115], v[150:153], v[228:231], v[112:115]
	v_mfma_f32_16x16x32_bf16 v[80:83], v[158:161], v[228:231], v[80:83]
	s_setprio 0
	s_setprio 1
	v_mfma_f32_16x16x32_bf16 v[64:67], v[184:187], v[200:203], v[64:67]
	v_mfma_f32_16x16x32_bf16 v[40:43], v[192:195], v[200:203], v[40:43]
	v_mfma_f32_16x16x32_bf16 v[56:59], v[184:187], v[208:211], v[56:59]
	v_mfma_f32_16x16x32_bf16 v[32:35], v[192:195], v[208:211], v[32:35]
	v_mfma_f32_16x16x32_bf16 v[52:55], v[184:187], v[216:219], v[52:55]
	v_mfma_f32_16x16x32_bf16 v[24:27], v[192:195], v[216:219], v[24:27]
	v_mfma_f32_16x16x32_bf16 v[48:51], v[184:187], v[224:227], v[48:51]
	v_mfma_f32_16x16x32_bf16 v[16:19], v[192:195], v[224:227], v[16:19]
	v_mfma_f32_16x16x32_bf16 v[64:67], v[188:191], v[204:207], v[64:67]
	v_mfma_f32_16x16x32_bf16 v[40:43], v[196:199], v[204:207], v[40:43]
	v_mfma_f32_16x16x32_bf16 v[56:59], v[188:191], v[212:215], v[56:59]
	v_mfma_f32_16x16x32_bf16 v[32:35], v[196:199], v[212:215], v[32:35]
	v_mfma_f32_16x16x32_bf16 v[52:55], v[188:191], v[220:223], v[52:55]
	v_mfma_f32_16x16x32_bf16 v[24:27], v[196:199], v[220:223], v[24:27]
	v_mfma_f32_16x16x32_bf16 v[48:51], v[188:191], v[228:231], v[48:51]
	v_mfma_f32_16x16x32_bf16 v[16:19], v[196:199], v[228:231], v[16:19]
	s_barrier
	s_setprio 0
	s_add_i32 s8, s17, s3
	s_mov_b32 m0, s8
	ds_read_b128 v[200:203], v166 offset:16384
	ds_read_b128 v[204:207], v166 offset:17408
	ds_read_b128 v[208:211], v166 offset:18432
	ds_read_b128 v[212:215], v166 offset:19456
	ds_read_b128 v[216:219], v166 offset:20480
	ds_read_b128 v[220:223], v166 offset:21504
	ds_read_b128 v[224:227], v166 offset:22528
	ds_read_b128 v[228:231], v166 offset:23552
	global_load_lds_dwordx4 v128, s[52:53]
	s_add_i32 m0, s8, 0x2000
	s_add_u32 s8, s52, 0x50000
	s_addc_u32 s9, s53, 0
	s_add_i32 s15, s15, s3
	global_load_lds_dwordx4 v138, s[52:53]
	s_mov_b32 m0, s15
	s_nop 0
	global_load_lds_dwordx4 v128, s[8:9]
	s_add_i32 m0, s15, 0x2000
	s_nop 0
	global_load_lds_dwordx4 v138, s[8:9]
	s_mov_b32 m0, s26
	s_nop 0
	global_load_lds_dwordx4 v128, s[54:55]
	s_mov_b32 m0, s27
	s_nop 0
	global_load_lds_dwordx4 v138, s[54:55]
	s_waitcnt vmcnt(8)
	s_waitcnt lgkmcnt(0)
	s_setprio 1
	s_barrier
	v_mfma_f32_16x16x32_bf16 v[108:111], v[146:149], v[200:203], v[108:111]
	v_mfma_f32_16x16x32_bf16 v[76:79], v[154:157], v[200:203], v[76:79]
	v_mfma_f32_16x16x32_bf16 v[104:107], v[146:149], v[208:211], v[104:107]
	v_mfma_f32_16x16x32_bf16 v[72:75], v[154:157], v[208:211], v[72:75]
	v_mfma_f32_16x16x32_bf16 v[100:103], v[146:149], v[216:219], v[100:103]
	v_mfma_f32_16x16x32_bf16 v[68:71], v[154:157], v[216:219], v[68:71]
	v_mfma_f32_16x16x32_bf16 v[96:99], v[146:149], v[224:227], v[96:99]
	v_mfma_f32_16x16x32_bf16 v[60:63], v[154:157], v[224:227], v[60:63]
	v_mfma_f32_16x16x32_bf16 v[108:111], v[150:153], v[204:207], v[108:111]
	v_mfma_f32_16x16x32_bf16 v[76:79], v[158:161], v[204:207], v[76:79]
	v_mfma_f32_16x16x32_bf16 v[104:107], v[150:153], v[212:215], v[104:107]
	v_mfma_f32_16x16x32_bf16 v[72:75], v[158:161], v[212:215], v[72:75]
	v_mfma_f32_16x16x32_bf16 v[100:103], v[150:153], v[220:223], v[100:103]
	v_mfma_f32_16x16x32_bf16 v[68:71], v[158:161], v[220:223], v[68:71]
	v_mfma_f32_16x16x32_bf16 v[96:99], v[150:153], v[228:231], v[96:99]
	v_mfma_f32_16x16x32_bf16 v[60:63], v[158:161], v[228:231], v[60:63]
	s_setprio 0
	s_setprio 1
	v_mfma_f32_16x16x32_bf16 v[44:47], v[184:187], v[200:203], v[44:47]
	v_mfma_f32_16x16x32_bf16 v[12:15], v[192:195], v[200:203], v[12:15]
	v_mfma_f32_16x16x32_bf16 v[36:39], v[184:187], v[208:211], v[36:39]
	v_mfma_f32_16x16x32_bf16 v[8:11], v[192:195], v[208:211], v[8:11]
	v_mfma_f32_16x16x32_bf16 v[28:31], v[184:187], v[216:219], v[28:31]
	v_mfma_f32_16x16x32_bf16 v[4:7], v[192:195], v[216:219], v[4:7]
	v_mfma_f32_16x16x32_bf16 v[20:23], v[184:187], v[224:227], v[20:23]
	v_mfma_f32_16x16x32_bf16 v[0:3], v[192:195], v[224:227], v[0:3]
	v_mfma_f32_16x16x32_bf16 v[44:47], v[188:191], v[204:207], v[44:47]
	v_mfma_f32_16x16x32_bf16 v[12:15], v[196:199], v[204:207], v[12:15]
	v_mfma_f32_16x16x32_bf16 v[36:39], v[188:191], v[212:215], v[36:39]
	v_mfma_f32_16x16x32_bf16 v[8:11], v[196:199], v[212:215], v[8:11]
	v_mfma_f32_16x16x32_bf16 v[28:31], v[188:191], v[220:223], v[28:31]
	v_mfma_f32_16x16x32_bf16 v[4:7], v[196:199], v[220:223], v[4:7]
	v_mfma_f32_16x16x32_bf16 v[20:23], v[188:191], v[228:231], v[20:23]
	v_mfma_f32_16x16x32_bf16 v[0:3], v[196:199], v[228:231], v[0:3]
	s_barrier
; #define PG8_STAGE(bufoff, gbase, voff) do { _Pragma("unroll") for (int _i = 0; _i < 2; ++_i) \
;         __builtin_amdgcn_global_load_lds((const unsigned*)((const char*)(gbase) + (voff)[_i]), (LAS unsigned*)(lds + (bufoff) + ldsw + _i * 8192), 16, 0, 0); } while (0)
; #define PG8_LDA(dst, b, h) do { _Pragma("unroll") for (int m = 0; m < 4; ++m) _Pragma("unroll") for (int k = 0; k < 2; ++k) dst[m][k] = *(const LAS bf16x8*)(lds + PG8_SA(b, h) + aoff + m * 2048 + k * 1024); } while (0)
; #define PG8_LDB(dst, b, h) do { _Pragma("unroll") for (int n = 0; n < 2; ++n) _Pragma("unroll") for (int k = 0; k < 2; ++k) dst[n][k] = *(const LAS bf16x8*)(lds + PG8_SB(b, h) + boff + n * 2048 + k * 1024); } while (0)
; #define PG8_MMA(ai, bj, At, Bt) do { __builtin_amdgcn_s_setprio(1); _Pragma("unroll") for (int m = 0; m < 4; ++m) _Pragma("unroll") for (int n = 0; n < 2; ++n) _Pragma("unroll") for (int k = 0; k < 2; ++k) \
;         acc[ai][bj][m][n] = __builtin_amdgcn_mfma_f32_16x16x32_bf16(Bt[n][k], At[m][k], acc[ai][bj][m][n], 0, 0, 0); __builtin_amdgcn_s_setprio(0); } while (0)
; #define PG8_WAIT_V(n) asm volatile("s_waitcnt vmcnt(" #n ")" ::: "memory")
; #define PG8_WAIT_L(n) asm volatile("s_waitcnt lgkmcnt(" #n ")" ::: "memory")
; #define PG8_BAR __builtin_amdgcn_s_barrier()
; #define PG8_SCHED __builtin_amdgcn_sched_barrier(0)
; template <class Epi, class Sched>
; __device__ __forceinline__ void gemm_phase(LAS unsigned char* lds, const int K, const Sched& S, const Epi& E) {
;     ...
;             PG8_LDB(B0, 1, 0); PG8_LDB(B1, 1, 1); PG8_SCHED; PG8_LDA(At, 1, 0); PG8_STAGE(PG8_SA(0, 1), a2 + hstep, voffA);
;             PG8_WAIT_V(8); PG8_WAIT_L(0); PG8_BAR; PG8_MMA(0, 0, At, B0); PG8_MMA(0, 1, At, B1); PG8_BAR; PG8_SCHED;
;             PG8_LDA(At, 1, 1); PG8_STAGE(PG8_SB(1, 0), b3, voffB); PG8_STAGE(PG8_SB(1, 1), b3 + hstep, voffB); PG8_STAGE(PG8_SA(1, 0), a3, voffA);
;             PG8_WAIT_V(8); PG8_WAIT_L(0); PG8_BAR; PG8_MMA(1, 0, At, B0); PG8_MMA(1, 1, At, B1); PG8_BAR; PG8_SCHED;
;         }
;         if (wr == 0) PG8_BAR;
	s_setprio 0
	s_add_i32 s15, 0, 0x18000
	s_add_i32 s17, 0, 0x1c000
	v_add_u32_e32 v158, s15, v164
	v_add_u32_e32 v167, s17, v164
	ds_read_b128 v[146:149], v158
	ds_read_b128 v[150:153], v158 offset:1024
	ds_read_b128 v[154:157], v158 offset:2048
	ds_read_b128 v[158:161], v158 offset:3072
	ds_read_b128 v[184:187], v167
	ds_read_b128 v[188:191], v167 offset:1024
	ds_read_b128 v[192:195], v167 offset:2048
	ds_read_b128 v[196:199], v167 offset:3072
	s_add_u32 s8, s54, 0x50000
	s_addc_u32 s9, s55, 0
	s_mov_b32 m0, s56
	ds_read_b128 v[200:203], v166 offset:32768
	ds_read_b128 v[204:207], v166 offset:33792
	ds_read_b128 v[208:211], v166 offset:34816
	ds_read_b128 v[212:215], v166 offset:35840
	ds_read_b128 v[216:219], v166 offset:36864
	ds_read_b128 v[220:223], v166 offset:37888
	ds_read_b128 v[224:227], v166 offset:38912
	ds_read_b128 v[228:231], v166 offset:39936
	global_load_lds_dwordx4 v128, s[8:9]
	s_mov_b32 m0, s57
	s_nop 0
	global_load_lds_dwordx4 v138, s[8:9]
	s_waitcnt vmcnt(8)
	s_waitcnt lgkmcnt(0)
	s_setprio 1
	s_barrier
	v_mfma_f32_16x16x32_bf16 v[124:127], v[146:149], v[200:203], v[124:127]
	v_mfma_f32_16x16x32_bf16 v[92:95], v[154:157], v[200:203], v[92:95]
	v_mfma_f32_16x16x32_bf16 v[120:123], v[146:149], v[208:211], v[120:123]
	v_mfma_f32_16x16x32_bf16 v[88:91], v[154:157], v[208:211], v[88:91]
	v_mfma_f32_16x16x32_bf16 v[116:119], v[146:149], v[216:219], v[116:119]
	v_mfma_f32_16x16x32_bf16 v[84:87], v[154:157], v[216:219], v[84:87]
	v_mfma_f32_16x16x32_bf16 v[112:115], v[146:149], v[224:227], v[112:115]
	v_mfma_f32_16x16x32_bf16 v[80:83], v[154:157], v[224:227], v[80:83]
	v_mfma_f32_16x16x32_bf16 v[124:127], v[150:153], v[204:207], v[124:127]
	v_mfma_f32_16x16x32_bf16 v[92:95], v[158:161], v[204:207], v[92:95]
	v_mfma_f32_16x16x32_bf16 v[120:123], v[150:153], v[212:215], v[120:123]
	v_mfma_f32_16x16x32_bf16 v[88:91], v[158:161], v[212:215], v[88:91]
	v_mfma_f32_16x16x32_bf16 v[116:119], v[150:153], v[220:223], v[116:119]
	v_mfma_f32_16x16x32_bf16 v[84:87], v[158:161], v[220:223], v[84:87]
	v_mfma_f32_16x16x32_bf16 v[112:115], v[150:153], v[228:231], v[112:115]
	v_mfma_f32_16x16x32_bf16 v[80:83], v[158:161], v[228:231], v[80:83]
	s_setprio 0
	s_setprio 1
	v_mfma_f32_16x16x32_bf16 v[64:67], v[184:187], v[200:203], v[64:67]
	v_mfma_f32_16x16x32_bf16 v[40:43], v[192:195], v[200:203], v[40:43]
	v_mfma_f32_16x16x32_bf16 v[56:59], v[184:187], v[208:211], v[56:59]
	v_mfma_f32_16x16x32_bf16 v[32:35], v[192:195], v[208:211], v[32:35]
	v_mfma_f32_16x16x32_bf16 v[52:55], v[184:187], v[216:219], v[52:55]
	v_mfma_f32_16x16x32_bf16 v[24:27], v[192:195], v[216:219], v[24:27]
	v_mfma_f32_16x16x32_bf16 v[48:51], v[184:187], v[224:227], v[48:51]
	v_mfma_f32_16x16x32_bf16 v[16:19], v[192:195], v[224:227], v[16:19]
	v_mfma_f32_16x16x32_bf16 v[64:67], v[188:191], v[204:207], v[64:67]
	v_mfma_f32_16x16x32_bf16 v[40:43], v[196:199], v[204:207], v[40:43]
	v_mfma_f32_16x16x32_bf16 v[56:59], v[188:191], v[212:215], v[56:59]
	v_mfma_f32_16x16x32_bf16 v[32:35], v[196:199], v[212:215], v[32:35]
	v_mfma_f32_16x16x32_bf16 v[52:55], v[188:191], v[220:223], v[52:55]
	v_mfma_f32_16x16x32_bf16 v[24:27], v[196:199], v[220:223], v[24:27]
	v_mfma_f32_16x16x32_bf16 v[48:51], v[188:191], v[228:231], v[48:51]
	v_mfma_f32_16x16x32_bf16 v[16:19], v[196:199], v[228:231], v[16:19]
	s_barrier
	s_setprio 0
	s_add_i32 s8, s15, s3
	s_mov_b32 m0, s8
	ds_read_b128 v[200:203], v166 offset:49152
	ds_read_b128 v[204:207], v166 offset:50176
	ds_read_b128 v[208:211], v166 offset:51200
	ds_read_b128 v[212:215], v166 offset:52224
	ds_read_b128 v[216:219], v166 offset:53248
	ds_read_b128 v[220:223], v166 offset:54272
	ds_read_b128 v[224:227], v166 offset:55296
	ds_read_b128 v[228:231], v166 offset:56320
	s_add_u32 s100, s52, s36
	s_addc_u32 s101, s53, s37
	global_load_lds_dwordx4 v128, s[100:101]
	s_add_i32 m0, s8, 0x2000
	s_add_u32 s8, s52, 0x50080
	s_addc_u32 s9, s53, 0
	s_add_i32 s15, s17, s3
	s_add_u32 s100, s52, s36
	s_addc_u32 s101, s53, s37
	global_load_lds_dwordx4 v138, s[100:101]
	s_mov_b32 m0, s15
	s_nop 0
	global_load_lds_dwordx4 v128, s[8:9]
	s_add_i32 m0, s15, 0x2000
	s_nop 0
	global_load_lds_dwordx4 v138, s[8:9]
	s_mov_b32 m0, s58
	s_nop 0
	s_add_u32 s100, s54, s36
	s_addc_u32 s101, s55, s37
	global_load_lds_dwordx4 v128, s[100:101]
	s_mov_b32 m0, s59
	s_nop 0
	s_add_u32 s100, s54, s36
	s_addc_u32 s101, s55, s37
	global_load_lds_dwordx4 v138, s[100:101]
	s_waitcnt vmcnt(8)
	s_waitcnt lgkmcnt(0)
	s_setprio 1
	s_barrier
	v_mfma_f32_16x16x32_bf16 v[108:111], v[146:149], v[200:203], v[108:111]
	v_mfma_f32_16x16x32_bf16 v[76:79], v[154:157], v[200:203], v[76:79]
	v_mfma_f32_16x16x32_bf16 v[104:107], v[146:149], v[208:211], v[104:107]
	v_mfma_f32_16x16x32_bf16 v[72:75], v[154:157], v[208:211], v[72:75]
	v_mfma_f32_16x16x32_bf16 v[100:103], v[146:149], v[216:219], v[100:103]
	v_mfma_f32_16x16x32_bf16 v[68:71], v[154:157], v[216:219], v[68:71]
	v_mfma_f32_16x16x32_bf16 v[96:99], v[146:149], v[224:227], v[96:99]
	v_mfma_f32_16x16x32_bf16 v[60:63], v[154:157], v[224:227], v[60:63]
	v_mfma_f32_16x16x32_bf16 v[108:111], v[150:153], v[204:207], v[108:111]
	v_mfma_f32_16x16x32_bf16 v[76:79], v[158:161], v[204:207], v[76:79]
	v_mfma_f32_16x16x32_bf16 v[104:107], v[150:153], v[212:215], v[104:107]
	v_mfma_f32_16x16x32_bf16 v[72:75], v[158:161], v[212:215], v[72:75]
	v_mfma_f32_16x16x32_bf16 v[100:103], v[150:153], v[220:223], v[100:103]
	v_mfma_f32_16x16x32_bf16 v[68:71], v[158:161], v[220:223], v[68:71]
	v_mfma_f32_16x16x32_bf16 v[96:99], v[150:153], v[228:231], v[96:99]
	v_mfma_f32_16x16x32_bf16 v[60:63], v[158:161], v[228:231], v[60:63]
	s_setprio 0
	s_setprio 1
	v_mfma_f32_16x16x32_bf16 v[44:47], v[184:187], v[200:203], v[44:47]
	v_mfma_f32_16x16x32_bf16 v[12:15], v[192:195], v[200:203], v[12:15]
	v_mfma_f32_16x16x32_bf16 v[36:39], v[184:187], v[208:211], v[36:39]
	v_mfma_f32_16x16x32_bf16 v[8:11], v[192:195], v[208:211], v[8:11]
	v_mfma_f32_16x16x32_bf16 v[28:31], v[184:187], v[216:219], v[28:31]
	v_mfma_f32_16x16x32_bf16 v[4:7], v[192:195], v[216:219], v[4:7]
	v_mfma_f32_16x16x32_bf16 v[20:23], v[184:187], v[224:227], v[20:23]
	v_mfma_f32_16x16x32_bf16 v[0:3], v[192:195], v[224:227], v[0:3]
	v_mfma_f32_16x16x32_bf16 v[44:47], v[188:191], v[204:207], v[44:47]
	v_mfma_f32_16x16x32_bf16 v[12:15], v[196:199], v[204:207], v[12:15]
	v_mfma_f32_16x16x32_bf16 v[36:39], v[188:191], v[212:215], v[36:39]
	v_mfma_f32_16x16x32_bf16 v[8:11], v[196:199], v[212:215], v[8:11]
	v_mfma_f32_16x16x32_bf16 v[28:31], v[188:191], v[220:223], v[28:31]
	v_mfma_f32_16x16x32_bf16 v[4:7], v[196:199], v[220:223], v[4:7]
	v_mfma_f32_16x16x32_bf16 v[20:23], v[188:191], v[228:231], v[20:23]
	v_mfma_f32_16x16x32_bf16 v[0:3], v[196:199], v[228:231], v[0:3]
	s_barrier
	s_setprio 0
	s_add_u32 s13, s13, 0x100
	s_addc_u32 s14, s14, 0
	s_cmp_ge_i32 s16, s2
	s_mov_b64 s[8:9], s[50:51]
	s_mov_b32 s15, s16
	s_cbranch_scc0 .LBB0_812
	s_and_b64 vcc, exec, s[40:41]
	s_cbranch_vccz .LBB0_815
	s_barrier

; #define PG8_STAGE(bufoff, gbase, voff) do { _Pragma("unroll") for (int _i = 0; _i < 2; ++_i) \
;         __builtin_amdgcn_global_load_lds((const unsigned*)((const char*)(gbase) + (voff)[_i]), (LAS unsigned*)(lds + (bufoff) + ldsw + _i * 8192), 16, 0, 0); } while (0)
; #define PG8_LDA(dst, b, h) do { _Pragma("unroll") for (int m = 0; m < 4; ++m) _Pragma("unroll") for (int k = 0; k < 2; ++k) dst[m][k] = *(const LAS bf16x8*)(lds + PG8_SA(b, h) + aoff + m * 2048 + k * 1024); } while (0)
; #define PG8_LDB(dst, b, h) do { _Pragma("unroll") for (int n = 0; n < 2; ++n) _Pragma("unroll") for (int k = 0; k < 2; ++k) dst[n][k] = *(const LAS bf16x8*)(lds + PG8_SB(b, h) + boff + n * 2048 + k * 1024); } while (0)
; #define PG8_MMA(ai, bj, At, Bt) do { __builtin_amdgcn_s_setprio(1); _Pragma("unroll") for (int m = 0; m < 4; ++m) _Pragma("unroll") for (int n = 0; n < 2; ++n) _Pragma("unroll") for (int k = 0; k < 2; ++k) \
;         acc[ai][bj][m][n] = __builtin_amdgcn_mfma_f32_16x16x32_bf16(Bt[n][k], At[m][k], acc[ai][bj][m][n], 0, 0, 0); __builtin_amdgcn_s_setprio(0); } while (0)
; #define PG8_WAIT_V(n) asm volatile("s_waitcnt vmcnt(" #n ")" ::: "memory")
; #define PG8_WAIT_L(n) asm volatile("s_waitcnt lgkmcnt(" #n ")" ::: "memory")
; #define PG8_BAR __builtin_amdgcn_s_barrier()
; #define PG8_SCHED __builtin_amdgcn_sched_barrier(0)
; template <class Epi, class Sched>
; __device__ __forceinline__ void gemm_phase(LAS unsigned char* lds, const int K, const Sched& S, const Epi& E) {
;     ...
;             const bool last = (t == nt - 2);
;             const char* a1 = cA + (size_t)(t + 1) * kstep;
;             const char* a2 = last ? nA : cA + (size_t)(t + 2) * kstep; const char* b2 = last ? nB : cB + (size_t)(t + 2) * kstep;
;             const char* a3 = a2 + kstep; const char* b3 = b2 + kstep;
;             PG8_LDB(B0, 0, 0); PG8_LDB(B1, 0, 1); PG8_SCHED; PG8_LDA(At, 0, 0); PG8_STAGE(PG8_SA(1, 1), a1 + hstep, voffA);
;             PG8_WAIT_V(8); PG8_WAIT_L(0); PG8_BAR; PG8_MMA(0, 0, At, B0); PG8_MMA(0, 1, At, B1); PG8_BAR; PG8_SCHED;
;             PG8_LDA(At, 0, 1); PG8_STAGE(PG8_SB(0, 0), b2, voffB); PG8_STAGE(PG8_SB(0, 1), b2 + hstep, voffB); PG8_STAGE(PG8_SA(0, 0), a2, voffA);
;             PG8_WAIT_V(8); PG8_WAIT_L(0); PG8_BAR; PG8_MMA(1, 0, At, B0); PG8_MMA(1, 1, At, B1); PG8_BAR; PG8_SCHED;
.LBB0_963:
	s_add_u32 s5, s56, 0xfffc0080
	s_addc_u32 s9, s57, -1
	s_add_i32 s10, 0, 0x10000
	s_cmp_eq_u32 s4, 12
	s_cselect_b32 s61, s53, s9
	s_cselect_b32 s60, s52, s5
	v_add_u32_e32 v150, s10, v153
	s_cselect_b32 s59, s55, s2
	s_cselect_b32 s58, s54, s1
	s_add_i32 s5, 0, 0x14000
	ds_read_b128 v[156:159], v150
	ds_read_b128 v[160:163], v150 offset:1024
	ds_read_b128 v[164:167], v150 offset:2048
	ds_read_b128 v[180:183], v150 offset:3072
	v_add_u32_e32 v150, s5, v153
	ds_read_b128 v[184:187], v150
	ds_read_b128 v[188:191], v150 offset:1024
	ds_read_b128 v[192:195], v150 offset:2048
	ds_read_b128 v[196:199], v150 offset:3072
	s_add_i32 m0, s66, 0xc000
	ds_read_b128 v[200:203], v154
	ds_read_b128 v[204:207], v154 offset:1024
	ds_read_b128 v[208:211], v154 offset:2048
	ds_read_b128 v[212:215], v154 offset:3072
	ds_read_b128 v[216:219], v154 offset:4096
	ds_read_b128 v[220:223], v154 offset:5120
	ds_read_b128 v[224:227], v154 offset:6144
	ds_read_b128 v[228:231], v154 offset:7168
	global_load_lds_dwordx4 v146, s[56:57]
	s_add_i32 m0, s66, 0xe000
	s_nop 0
	global_load_lds_dwordx4 v148, s[56:57]
	s_waitcnt vmcnt(8)
	s_waitcnt lgkmcnt(0)
	s_setprio 1
	s_barrier
	v_mfma_f32_16x16x32_bf16 v[124:127], v[156:159], v[200:203], v[124:127]
	v_mfma_f32_16x16x32_bf16 v[116:119], v[164:167], v[200:203], v[116:119]
	v_mfma_f32_16x16x32_bf16 v[108:111], v[156:159], v[208:211], v[108:111]
	v_mfma_f32_16x16x32_bf16 v[100:103], v[164:167], v[208:211], v[100:103]
	v_mfma_f32_16x16x32_bf16 v[92:95], v[156:159], v[216:219], v[92:95]
	v_mfma_f32_16x16x32_bf16 v[84:87], v[164:167], v[216:219], v[84:87]
	v_mfma_f32_16x16x32_bf16 v[76:79], v[156:159], v[224:227], v[76:79]
	v_mfma_f32_16x16x32_bf16 v[68:71], v[164:167], v[224:227], v[68:71]
	v_mfma_f32_16x16x32_bf16 v[124:127], v[160:163], v[204:207], v[124:127]
	v_mfma_f32_16x16x32_bf16 v[116:119], v[180:183], v[204:207], v[116:119]
	v_mfma_f32_16x16x32_bf16 v[108:111], v[160:163], v[212:215], v[108:111]
	v_mfma_f32_16x16x32_bf16 v[100:103], v[180:183], v[212:215], v[100:103]
	v_mfma_f32_16x16x32_bf16 v[92:95], v[160:163], v[220:223], v[92:95]
	v_mfma_f32_16x16x32_bf16 v[84:87], v[180:183], v[220:223], v[84:87]
	v_mfma_f32_16x16x32_bf16 v[76:79], v[160:163], v[228:231], v[76:79]
	v_mfma_f32_16x16x32_bf16 v[68:71], v[180:183], v[228:231], v[68:71]
	s_setprio 0
	s_setprio 1
	v_mfma_f32_16x16x32_bf16 v[120:123], v[184:187], v[200:203], v[120:123]
	v_mfma_f32_16x16x32_bf16 v[112:115], v[192:195], v[200:203], v[112:115]
	v_mfma_f32_16x16x32_bf16 v[104:107], v[184:187], v[208:211], v[104:107]
	v_mfma_f32_16x16x32_bf16 v[96:99], v[192:195], v[208:211], v[96:99]
	v_mfma_f32_16x16x32_bf16 v[88:91], v[184:187], v[216:219], v[88:91]
	v_mfma_f32_16x16x32_bf16 v[80:83], v[192:195], v[216:219], v[80:83]
	v_mfma_f32_16x16x32_bf16 v[72:75], v[184:187], v[224:227], v[72:75]
	v_mfma_f32_16x16x32_bf16 v[64:67], v[192:195], v[224:227], v[64:67]
	v_mfma_f32_16x16x32_bf16 v[120:123], v[188:191], v[204:207], v[120:123]
	v_mfma_f32_16x16x32_bf16 v[112:115], v[196:199], v[204:207], v[112:115]
	v_mfma_f32_16x16x32_bf16 v[104:107], v[188:191], v[212:215], v[104:107]
	v_mfma_f32_16x16x32_bf16 v[96:99], v[196:199], v[212:215], v[96:99]
	v_mfma_f32_16x16x32_bf16 v[88:91], v[188:191], v[220:223], v[88:91]
	v_mfma_f32_16x16x32_bf16 v[80:83], v[196:199], v[220:223], v[80:83]
	v_mfma_f32_16x16x32_bf16 v[72:75], v[188:191], v[228:231], v[72:75]
	v_mfma_f32_16x16x32_bf16 v[64:67], v[196:199], v[228:231], v[64:67]
	s_barrier
	s_setprio 0
	s_add_i32 s9, s10, s63
	s_mov_b32 m0, s9
	ds_read_b128 v[200:203], v154 offset:16384
	ds_read_b128 v[204:207], v154 offset:17408
	ds_read_b128 v[208:211], v154 offset:18432
	ds_read_b128 v[212:215], v154 offset:19456
	ds_read_b128 v[216:219], v154 offset:20480
	ds_read_b128 v[220:223], v154 offset:21504
	ds_read_b128 v[224:227], v154 offset:22528
	ds_read_b128 v[228:231], v154 offset:23552
	global_load_lds_dwordx4 v142, s[58:59]
	s_add_i32 m0, s9, 0x2000
	s_add_u32 s10, s58, 0x40000
	s_addc_u32 s11, s59, 0
	s_add_i32 s5, s5, s63
	global_load_lds_dwordx4 v138, s[58:59]
	s_mov_b32 m0, s5
	s_nop 0
	global_load_lds_dwordx4 v142, s[10:11]
	s_add_i32 m0, s5, 0x2000
	s_nop 0
	global_load_lds_dwordx4 v138, s[10:11]
	s_mov_b32 m0, s66
	s_nop 0
	global_load_lds_dwordx4 v144, s[60:61]
	s_mov_b32 m0, s67
	s_nop 0
	global_load_lds_dwordx4 v140, s[60:61]
	s_waitcnt vmcnt(8)
	s_waitcnt lgkmcnt(0)
	s_setprio 1
	s_barrier
	v_mfma_f32_16x16x32_bf16 v[60:63], v[156:159], v[200:203], v[60:63]
	v_mfma_f32_16x16x32_bf16 v[52:55], v[164:167], v[200:203], v[52:55]
	v_mfma_f32_16x16x32_bf16 v[44:47], v[156:159], v[208:211], v[44:47]
	v_mfma_f32_16x16x32_bf16 v[36:39], v[164:167], v[208:211], v[36:39]
	v_mfma_f32_16x16x32_bf16 v[28:31], v[156:159], v[216:219], v[28:31]
	v_mfma_f32_16x16x32_bf16 v[20:23], v[164:167], v[216:219], v[20:23]
	v_mfma_f32_16x16x32_bf16 v[12:15], v[156:159], v[224:227], v[12:15]
	v_mfma_f32_16x16x32_bf16 v[4:7], v[164:167], v[224:227], v[4:7]
	v_mfma_f32_16x16x32_bf16 v[60:63], v[160:163], v[204:207], v[60:63]
	v_mfma_f32_16x16x32_bf16 v[52:55], v[180:183], v[204:207], v[52:55]
	v_mfma_f32_16x16x32_bf16 v[44:47], v[160:163], v[212:215], v[44:47]
	v_mfma_f32_16x16x32_bf16 v[36:39], v[180:183], v[212:215], v[36:39]
	v_mfma_f32_16x16x32_bf16 v[28:31], v[160:163], v[220:223], v[28:31]
	v_mfma_f32_16x16x32_bf16 v[20:23], v[180:183], v[220:223], v[20:23]
	v_mfma_f32_16x16x32_bf16 v[12:15], v[160:163], v[228:231], v[12:15]
	v_mfma_f32_16x16x32_bf16 v[4:7], v[180:183], v[228:231], v[4:7]
	s_setprio 0
	s_setprio 1
	v_mfma_f32_16x16x32_bf16 v[56:59], v[184:187], v[200:203], v[56:59]
	v_mfma_f32_16x16x32_bf16 v[48:51], v[192:195], v[200:203], v[48:51]
	v_mfma_f32_16x16x32_bf16 v[40:43], v[184:187], v[208:211], v[40:43]
	v_mfma_f32_16x16x32_bf16 v[32:35], v[192:195], v[208:211], v[32:35]
	v_mfma_f32_16x16x32_bf16 v[24:27], v[184:187], v[216:219], v[24:27]
	v_mfma_f32_16x16x32_bf16 v[16:19], v[192:195], v[216:219], v[16:19]
	v_mfma_f32_16x16x32_bf16 v[8:11], v[184:187], v[224:227], v[8:11]
	v_mfma_f32_16x16x32_bf16 v[0:3], v[192:195], v[224:227], v[0:3]
	v_mfma_f32_16x16x32_bf16 v[56:59], v[188:191], v[204:207], v[56:59]
	v_mfma_f32_16x16x32_bf16 v[48:51], v[196:199], v[204:207], v[48:51]
	v_mfma_f32_16x16x32_bf16 v[40:43], v[188:191], v[212:215], v[40:43]
	v_mfma_f32_16x16x32_bf16 v[32:35], v[196:199], v[212:215], v[32:35]
	v_mfma_f32_16x16x32_bf16 v[24:27], v[188:191], v[220:223], v[24:27]
	v_mfma_f32_16x16x32_bf16 v[16:19], v[196:199], v[220:223], v[16:19]
	v_mfma_f32_16x16x32_bf16 v[8:11], v[188:191], v[228:231], v[8:11]
	v_mfma_f32_16x16x32_bf16 v[0:3], v[196:199], v[228:231], v[0:3]
	s_barrier
; #define PG8_STAGE(bufoff, gbase, voff) do { _Pragma("unroll") for (int _i = 0; _i < 2; ++_i) \
;         __builtin_amdgcn_global_load_lds((const unsigned*)((const char*)(gbase) + (voff)[_i]), (LAS unsigned*)(lds + (bufoff) + ldsw + _i * 8192), 16, 0, 0); } while (0)
; #define PG8_LDA(dst, b, h) do { _Pragma("unroll") for (int m = 0; m < 4; ++m) _Pragma("unroll") for (int k = 0; k < 2; ++k) dst[m][k] = *(const LAS bf16x8*)(lds + PG8_SA(b, h) + aoff + m * 2048 + k * 1024); } while (0)
; #define PG8_LDB(dst, b, h) do { _Pragma("unroll") for (int n = 0; n < 2; ++n) _Pragma("unroll") for (int k = 0; k < 2; ++k) dst[n][k] = *(const LAS bf16x8*)(lds + PG8_SB(b, h) + boff + n * 2048 + k * 1024); } while (0)
; #define PG8_MMA(ai, bj, At, Bt) do { __builtin_amdgcn_s_setprio(1); _Pragma("unroll") for (int m = 0; m < 4; ++m) _Pragma("unroll") for (int n = 0; n < 2; ++n) _Pragma("unroll") for (int k = 0; k < 2; ++k) \
;         acc[ai][bj][m][n] = __builtin_amdgcn_mfma_f32_16x16x32_bf16(Bt[n][k], At[m][k], acc[ai][bj][m][n], 0, 0, 0); __builtin_amdgcn_s_setprio(0); } while (0)
; #define PG8_WAIT_V(n) asm volatile("s_waitcnt vmcnt(" #n ")" ::: "memory")
; #define PG8_WAIT_L(n) asm volatile("s_waitcnt lgkmcnt(" #n ")" ::: "memory")
; #define PG8_BAR __builtin_amdgcn_s_barrier()
; #define PG8_SCHED __builtin_amdgcn_sched_barrier(0)
; template <class Epi, class Sched>
; __device__ __forceinline__ void gemm_phase(LAS unsigned char* lds, const int K, const Sched& S, const Epi& E) {
;     ...
;             PG8_LDB(B0, 1, 0); PG8_LDB(B1, 1, 1); PG8_SCHED; PG8_LDA(At, 1, 0); PG8_STAGE(PG8_SA(0, 1), a2 + hstep, voffA);
;             PG8_WAIT_V(8); PG8_WAIT_L(0); PG8_BAR; PG8_MMA(0, 0, At, B0); PG8_MMA(0, 1, At, B1); PG8_BAR; PG8_SCHED;
;             PG8_LDA(At, 1, 1); PG8_STAGE(PG8_SB(1, 0), b3, voffB); PG8_STAGE(PG8_SB(1, 1), b3 + hstep, voffB); PG8_STAGE(PG8_SA(1, 0), a3, voffA);
;             PG8_WAIT_V(8); PG8_WAIT_L(0); PG8_BAR; PG8_MMA(1, 0, At, B0); PG8_MMA(1, 1, At, B1); PG8_BAR; PG8_SCHED;
;         }
;         if (wr == 0) PG8_BAR;
	s_setprio 0
	s_add_i32 s5, 0, 0x18000
	v_add_u32_e32 v155, s5, v153
	s_add_i32 s9, 0, 0x1c000
	ds_read_b128 v[156:159], v155
	ds_read_b128 v[160:163], v155 offset:1024
	ds_read_b128 v[164:167], v155 offset:2048
	ds_read_b128 v[180:183], v155 offset:3072
	v_add_u32_e32 v155, s9, v153
	ds_read_b128 v[184:187], v155
	ds_read_b128 v[188:191], v155 offset:1024
	ds_read_b128 v[192:195], v155 offset:2048
	ds_read_b128 v[196:199], v155 offset:3072
	s_add_u32 s10, s60, 0x40000
	s_addc_u32 s11, s61, 0
	s_mov_b32 m0, s68
	ds_read_b128 v[200:203], v154 offset:32768
	ds_read_b128 v[204:207], v154 offset:33792
	ds_read_b128 v[208:211], v154 offset:34816
	ds_read_b128 v[212:215], v154 offset:35840
	ds_read_b128 v[216:219], v154 offset:36864
	ds_read_b128 v[220:223], v154 offset:37888
	ds_read_b128 v[224:227], v154 offset:38912
	ds_read_b128 v[228:231], v154 offset:39936
	global_load_lds_dwordx4 v144, s[10:11]
	s_mov_b32 m0, s69
	s_nop 0
	global_load_lds_dwordx4 v140, s[10:11]
	s_waitcnt vmcnt(8)
	s_waitcnt lgkmcnt(0)
	s_setprio 1
	s_barrier
	v_mfma_f32_16x16x32_bf16 v[124:127], v[156:159], v[200:203], v[124:127]
	v_mfma_f32_16x16x32_bf16 v[116:119], v[164:167], v[200:203], v[116:119]
	v_mfma_f32_16x16x32_bf16 v[108:111], v[156:159], v[208:211], v[108:111]
	v_mfma_f32_16x16x32_bf16 v[100:103], v[164:167], v[208:211], v[100:103]
	v_mfma_f32_16x16x32_bf16 v[92:95], v[156:159], v[216:219], v[92:95]
	v_mfma_f32_16x16x32_bf16 v[84:87], v[164:167], v[216:219], v[84:87]
	v_mfma_f32_16x16x32_bf16 v[76:79], v[156:159], v[224:227], v[76:79]
	v_mfma_f32_16x16x32_bf16 v[68:71], v[164:167], v[224:227], v[68:71]
	v_mfma_f32_16x16x32_bf16 v[124:127], v[160:163], v[204:207], v[124:127]
	v_mfma_f32_16x16x32_bf16 v[116:119], v[180:183], v[204:207], v[116:119]
	v_mfma_f32_16x16x32_bf16 v[108:111], v[160:163], v[212:215], v[108:111]
	v_mfma_f32_16x16x32_bf16 v[100:103], v[180:183], v[212:215], v[100:103]
	v_mfma_f32_16x16x32_bf16 v[92:95], v[160:163], v[220:223], v[92:95]
	v_mfma_f32_16x16x32_bf16 v[84:87], v[180:183], v[220:223], v[84:87]
	v_mfma_f32_16x16x32_bf16 v[76:79], v[160:163], v[228:231], v[76:79]
	v_mfma_f32_16x16x32_bf16 v[68:71], v[180:183], v[228:231], v[68:71]
	s_setprio 0
	s_setprio 1
	v_mfma_f32_16x16x32_bf16 v[120:123], v[184:187], v[200:203], v[120:123]
	v_mfma_f32_16x16x32_bf16 v[112:115], v[192:195], v[200:203], v[112:115]
	v_mfma_f32_16x16x32_bf16 v[104:107], v[184:187], v[208:211], v[104:107]
	v_mfma_f32_16x16x32_bf16 v[96:99], v[192:195], v[208:211], v[96:99]
	v_mfma_f32_16x16x32_bf16 v[88:91], v[184:187], v[216:219], v[88:91]
	v_mfma_f32_16x16x32_bf16 v[80:83], v[192:195], v[216:219], v[80:83]
	v_mfma_f32_16x16x32_bf16 v[72:75], v[184:187], v[224:227], v[72:75]
	v_mfma_f32_16x16x32_bf16 v[64:67], v[192:195], v[224:227], v[64:67]
	v_mfma_f32_16x16x32_bf16 v[120:123], v[188:191], v[204:207], v[120:123]
	v_mfma_f32_16x16x32_bf16 v[112:115], v[196:199], v[204:207], v[112:115]
	v_mfma_f32_16x16x32_bf16 v[104:107], v[188:191], v[212:215], v[104:107]
	v_mfma_f32_16x16x32_bf16 v[96:99], v[196:199], v[212:215], v[96:99]
	v_mfma_f32_16x16x32_bf16 v[88:91], v[188:191], v[220:223], v[88:91]
	v_mfma_f32_16x16x32_bf16 v[80:83], v[196:199], v[220:223], v[80:83]
	v_mfma_f32_16x16x32_bf16 v[72:75], v[188:191], v[228:231], v[72:75]
	v_mfma_f32_16x16x32_bf16 v[64:67], v[196:199], v[228:231], v[64:67]
	s_barrier
	s_setprio 0
	s_add_i32 s5, s5, s63
	s_mov_b32 m0, s5
	ds_read_b128 v[200:203], v154 offset:49152
	ds_read_b128 v[204:207], v154 offset:50176
	ds_read_b128 v[208:211], v154 offset:51200
	ds_read_b128 v[212:215], v154 offset:52224
	ds_read_b128 v[216:219], v154 offset:53248
	ds_read_b128 v[220:223], v154 offset:54272
	ds_read_b128 v[224:227], v154 offset:55296
	ds_read_b128 v[228:231], v154 offset:56320
	s_add_u32 s100, s58, s36
	s_addc_u32 s101, s59, s37
	global_load_lds_dwordx4 v142, s[100:101]
	s_add_i32 m0, s5, 0x2000
	s_add_u32 s10, s58, 0x40080
	s_addc_u32 s11, s59, 0
	s_add_i32 s5, s9, s63
	s_add_u32 s100, s58, s36
	s_addc_u32 s101, s59, s37
	global_load_lds_dwordx4 v138, s[100:101]
	s_mov_b32 m0, s5
	s_nop 0
	global_load_lds_dwordx4 v142, s[10:11]
	s_add_i32 m0, s5, 0x2000
	s_nop 0
	global_load_lds_dwordx4 v138, s[10:11]
	s_mov_b32 m0, s70
	s_nop 0
	s_add_u32 s100, s60, s36
	s_addc_u32 s101, s61, s37
	global_load_lds_dwordx4 v144, s[100:101]
	s_mov_b32 m0, s71
	s_nop 0
	s_add_u32 s100, s60, s36
	s_addc_u32 s101, s61, s37
	global_load_lds_dwordx4 v140, s[100:101]
	s_waitcnt vmcnt(8)
	s_waitcnt lgkmcnt(0)
	s_setprio 1
	s_barrier
	v_mfma_f32_16x16x32_bf16 v[60:63], v[156:159], v[200:203], v[60:63]
	v_mfma_f32_16x16x32_bf16 v[52:55], v[164:167], v[200:203], v[52:55]
	v_mfma_f32_16x16x32_bf16 v[44:47], v[156:159], v[208:211], v[44:47]
	v_mfma_f32_16x16x32_bf16 v[36:39], v[164:167], v[208:211], v[36:39]
	v_mfma_f32_16x16x32_bf16 v[28:31], v[156:159], v[216:219], v[28:31]
	v_mfma_f32_16x16x32_bf16 v[20:23], v[164:167], v[216:219], v[20:23]
	v_mfma_f32_16x16x32_bf16 v[12:15], v[156:159], v[224:227], v[12:15]
	v_mfma_f32_16x16x32_bf16 v[4:7], v[164:167], v[224:227], v[4:7]
	v_mfma_f32_16x16x32_bf16 v[60:63], v[160:163], v[204:207], v[60:63]
	v_mfma_f32_16x16x32_bf16 v[52:55], v[180:183], v[204:207], v[52:55]
	v_mfma_f32_16x16x32_bf16 v[44:47], v[160:163], v[212:215], v[44:47]
	v_mfma_f32_16x16x32_bf16 v[36:39], v[180:183], v[212:215], v[36:39]
	v_mfma_f32_16x16x32_bf16 v[28:31], v[160:163], v[220:223], v[28:31]
	v_mfma_f32_16x16x32_bf16 v[20:23], v[180:183], v[220:223], v[20:23]
	v_mfma_f32_16x16x32_bf16 v[12:15], v[160:163], v[228:231], v[12:15]
	v_mfma_f32_16x16x32_bf16 v[4:7], v[180:183], v[228:231], v[4:7]
	s_setprio 0
	s_setprio 1
	v_mfma_f32_16x16x32_bf16 v[56:59], v[184:187], v[200:203], v[56:59]
	v_mfma_f32_16x16x32_bf16 v[48:51], v[192:195], v[200:203], v[48:51]
	v_mfma_f32_16x16x32_bf16 v[40:43], v[184:187], v[208:211], v[40:43]
	v_mfma_f32_16x16x32_bf16 v[32:35], v[192:195], v[208:211], v[32:35]
	v_mfma_f32_16x16x32_bf16 v[24:27], v[184:187], v[216:219], v[24:27]
	v_mfma_f32_16x16x32_bf16 v[16:19], v[192:195], v[216:219], v[16:19]
	v_mfma_f32_16x16x32_bf16 v[8:11], v[184:187], v[224:227], v[8:11]
	v_mfma_f32_16x16x32_bf16 v[0:3], v[192:195], v[224:227], v[0:3]
	v_mfma_f32_16x16x32_bf16 v[56:59], v[188:191], v[204:207], v[56:59]
	v_mfma_f32_16x16x32_bf16 v[48:51], v[196:199], v[204:207], v[48:51]
	v_mfma_f32_16x16x32_bf16 v[40:43], v[188:191], v[212:215], v[40:43]
	v_mfma_f32_16x16x32_bf16 v[32:35], v[196:199], v[212:215], v[32:35]
	v_mfma_f32_16x16x32_bf16 v[24:27], v[188:191], v[220:223], v[24:27]
	v_mfma_f32_16x16x32_bf16 v[16:19], v[196:199], v[220:223], v[16:19]
	v_mfma_f32_16x16x32_bf16 v[8:11], v[188:191], v[228:231], v[8:11]
	v_mfma_f32_16x16x32_bf16 v[0:3], v[196:199], v[228:231], v[0:3]
	s_barrier
	s_setprio 0
	s_add_i32 s4, s4, 2
	s_add_u32 s56, s56, 0x100
	s_addc_u32 s57, s57, 0
	s_add_u32 s1, s1, 0x100
	s_addc_u32 s2, s2, 0
	s_cmp_gt_u32 s4, 13
	s_cbranch_scc0 .LBB0_963
	s_and_b64 vcc, exec, s[46:47]
	s_cbranch_vccz .LBB0_966
	s_barrier

; #define PG8_STAGE(bufoff, gbase, voff) do { _Pragma("unroll") for (int _i = 0; _i < 2; ++_i) \
;         __builtin_amdgcn_global_load_lds((const unsigned*)((const char*)(gbase) + (voff)[_i]), (LAS unsigned*)(lds + (bufoff) + ldsw + _i * 8192), 16, 0, 0); } while (0)
; #define PG8_LDA(dst, b, h) do { _Pragma("unroll") for (int m = 0; m < 4; ++m) _Pragma("unroll") for (int k = 0; k < 2; ++k) dst[m][k] = *(const LAS bf16x8*)(lds + PG8_SA(b, h) + aoff + m * 2048 + k * 1024); } while (0)
; #define PG8_LDB(dst, b, h) do { _Pragma("unroll") for (int n = 0; n < 2; ++n) _Pragma("unroll") for (int k = 0; k < 2; ++k) dst[n][k] = *(const LAS bf16x8*)(lds + PG8_SB(b, h) + boff + n * 2048 + k * 1024); } while (0)
; #define PG8_MMA(ai, bj, At, Bt) do { __builtin_amdgcn_s_setprio(1); _Pragma("unroll") for (int m = 0; m < 4; ++m) _Pragma("unroll") for (int n = 0; n < 2; ++n) _Pragma("unroll") for (int k = 0; k < 2; ++k) \
;         acc[ai][bj][m][n] = __builtin_amdgcn_mfma_f32_16x16x32_bf16(Bt[n][k], At[m][k], acc[ai][bj][m][n], 0, 0, 0); __builtin_amdgcn_s_setprio(0); } while (0)
; #define PG8_WAIT_V(n) asm volatile("s_waitcnt vmcnt(" #n ")" ::: "memory")
; #define PG8_WAIT_L(n) asm volatile("s_waitcnt lgkmcnt(" #n ")" ::: "memory")
; #define PG8_BAR __builtin_amdgcn_s_barrier()
; #define PG8_SCHED __builtin_amdgcn_sched_barrier(0)
; template <class Epi, class Sched>
; __device__ __forceinline__ void gemm_phase(LAS unsigned char* lds, const int K, const Sched& S, const Epi& E) {
;     ...
;             const bool last = (t == nt - 2);
;             const char* a1 = cA + (size_t)(t + 1) * kstep;
;             const char* a2 = last ? nA : cA + (size_t)(t + 2) * kstep; const char* b2 = last ? nB : cB + (size_t)(t + 2) * kstep;
;             const char* a3 = a2 + kstep; const char* b3 = b2 + kstep;
;             PG8_LDB(B0, 0, 0); PG8_LDB(B1, 0, 1); PG8_SCHED; PG8_LDA(At, 0, 0); PG8_STAGE(PG8_SA(1, 1), a1 + hstep, voffA);
;             PG8_WAIT_V(8); PG8_WAIT_L(0); PG8_BAR; PG8_MMA(0, 0, At, B0); PG8_MMA(0, 1, At, B1); PG8_BAR; PG8_SCHED;
;             PG8_LDA(At, 0, 1); PG8_STAGE(PG8_SB(0, 0), b2, voffB); PG8_STAGE(PG8_SB(0, 1), b2 + hstep, voffB); PG8_STAGE(PG8_SA(0, 0), a2, voffA);
;             PG8_WAIT_V(8); PG8_WAIT_L(0); PG8_BAR; PG8_MMA(1, 0, At, B0); PG8_MMA(1, 1, At, B1); PG8_BAR; PG8_SCHED;
.LBB0_1073:
	s_add_i32 s13, s12, 2
	s_add_u32 s52, s8, 0x100
	s_addc_u32 s53, s9, 0
	s_add_i32 s14, 0, 0x10000
	s_cmp_eq_u32 s5, s12
	s_cselect_b32 s57, s0, s53
	s_cselect_b32 s56, s1, s52
	s_cselect_b32 s55, s2, s11
	s_cselect_b32 s54, s4, s10
	s_add_i32 s12, 0, 0x14000
	v_add_u32_e32 v158, s14, v164
	v_add_u32_e32 v162, s12, v164
	ds_read_b128 v[146:149], v158
	ds_read_b128 v[150:153], v158 offset:1024
	ds_read_b128 v[154:157], v158 offset:2048
	ds_read_b128 v[158:161], v158 offset:3072
	ds_read_b128 v[180:183], v162
	ds_read_b128 v[184:187], v162 offset:1024
	ds_read_b128 v[188:191], v162 offset:2048
	ds_read_b128 v[192:195], v162 offset:3072
	v_lshl_add_u64 v[162:163], s[8:9], 0, v[142:143]
	s_add_i32 m0, s61, 0xc000
	ds_read_b128 v[196:199], v166
	ds_read_b128 v[200:203], v166 offset:1024
	ds_read_b128 v[204:207], v166 offset:2048
	ds_read_b128 v[208:211], v166 offset:3072
	ds_read_b128 v[212:215], v166 offset:4096
	ds_read_b128 v[216:219], v166 offset:5120
	ds_read_b128 v[220:223], v166 offset:6144
	ds_read_b128 v[224:227], v166 offset:7168
	global_load_lds_dwordx4 v[162:163], off
	v_lshl_add_u64 v[162:163], s[8:9], 0, v[144:145]
	s_add_i32 m0, s61, 0xe000
	s_nop 0
	global_load_lds_dwordx4 v[162:163], off
	s_waitcnt vmcnt(8)
	s_waitcnt lgkmcnt(0)
	s_setprio 1
	s_barrier
	v_mfma_f32_16x16x32_bf16 v[124:127], v[146:149], v[196:199], v[124:127]
	v_mfma_f32_16x16x32_bf16 v[92:95], v[154:157], v[196:199], v[92:95]
	v_mfma_f32_16x16x32_bf16 v[120:123], v[146:149], v[204:207], v[120:123]
	v_mfma_f32_16x16x32_bf16 v[88:91], v[154:157], v[204:207], v[88:91]
	v_mfma_f32_16x16x32_bf16 v[116:119], v[146:149], v[212:215], v[116:119]
	v_mfma_f32_16x16x32_bf16 v[84:87], v[154:157], v[212:215], v[84:87]
	v_mfma_f32_16x16x32_bf16 v[112:115], v[146:149], v[220:223], v[112:115]
	v_mfma_f32_16x16x32_bf16 v[80:83], v[154:157], v[220:223], v[80:83]
	v_mfma_f32_16x16x32_bf16 v[124:127], v[150:153], v[200:203], v[124:127]
	v_mfma_f32_16x16x32_bf16 v[92:95], v[158:161], v[200:203], v[92:95]
	v_mfma_f32_16x16x32_bf16 v[120:123], v[150:153], v[208:211], v[120:123]
	v_mfma_f32_16x16x32_bf16 v[88:91], v[158:161], v[208:211], v[88:91]
	v_mfma_f32_16x16x32_bf16 v[116:119], v[150:153], v[216:219], v[116:119]
	v_mfma_f32_16x16x32_bf16 v[84:87], v[158:161], v[216:219], v[84:87]
	v_mfma_f32_16x16x32_bf16 v[112:115], v[150:153], v[224:227], v[112:115]
	v_mfma_f32_16x16x32_bf16 v[80:83], v[158:161], v[224:227], v[80:83]
	s_setprio 0
	s_setprio 1
	v_mfma_f32_16x16x32_bf16 v[60:63], v[180:183], v[196:199], v[60:63]
	v_mfma_f32_16x16x32_bf16 v[28:31], v[188:191], v[196:199], v[28:31]
	v_mfma_f32_16x16x32_bf16 v[56:59], v[180:183], v[204:207], v[56:59]
	v_mfma_f32_16x16x32_bf16 v[24:27], v[188:191], v[204:207], v[24:27]
	v_mfma_f32_16x16x32_bf16 v[52:55], v[180:183], v[212:215], v[52:55]
	v_mfma_f32_16x16x32_bf16 v[20:23], v[188:191], v[212:215], v[20:23]
	v_mfma_f32_16x16x32_bf16 v[48:51], v[180:183], v[220:223], v[48:51]
	v_mfma_f32_16x16x32_bf16 v[16:19], v[188:191], v[220:223], v[16:19]
	v_mfma_f32_16x16x32_bf16 v[60:63], v[184:187], v[200:203], v[60:63]
	v_mfma_f32_16x16x32_bf16 v[28:31], v[192:195], v[200:203], v[28:31]
	v_mfma_f32_16x16x32_bf16 v[56:59], v[184:187], v[208:211], v[56:59]
	v_mfma_f32_16x16x32_bf16 v[24:27], v[192:195], v[208:211], v[24:27]
	v_mfma_f32_16x16x32_bf16 v[52:55], v[184:187], v[216:219], v[52:55]
	v_mfma_f32_16x16x32_bf16 v[20:23], v[192:195], v[216:219], v[20:23]
	v_mfma_f32_16x16x32_bf16 v[48:51], v[184:187], v[224:227], v[48:51]
	v_mfma_f32_16x16x32_bf16 v[16:19], v[192:195], v[224:227], v[16:19]
	s_barrier
	s_setprio 0
	s_add_i32 s8, s14, s60
	s_mov_b32 m0, s8
	ds_read_b128 v[196:199], v166 offset:16384
	ds_read_b128 v[200:203], v166 offset:17408
	ds_read_b128 v[204:207], v166 offset:18432
	ds_read_b128 v[208:211], v166 offset:19456
	ds_read_b128 v[212:215], v166 offset:20480
	ds_read_b128 v[216:219], v166 offset:21504
	ds_read_b128 v[220:223], v166 offset:22528
	ds_read_b128 v[224:227], v166 offset:23552
	global_load_lds_dwordx4 v128, s[54:55]
	s_add_i32 m0, s8, 0x2000
	s_add_u32 s8, s54, 0xb0000
	s_addc_u32 s9, s55, 0
	s_add_i32 s12, s12, s60
	global_load_lds_dwordx4 v138, s[54:55]
	s_mov_b32 m0, s12
	s_nop 0
	global_load_lds_dwordx4 v128, s[8:9]
	s_add_i32 m0, s12, 0x2000
	s_nop 0
	global_load_lds_dwordx4 v138, s[8:9]
	s_mov_b32 m0, s61
	s_nop 0
	global_load_lds_dwordx4 v128, s[56:57]
	s_mov_b32 m0, s63
	s_nop 0
	global_load_lds_dwordx4 v138, s[56:57]
	s_waitcnt vmcnt(8)
	s_waitcnt lgkmcnt(0)
	s_setprio 1
	s_barrier
	v_mfma_f32_16x16x32_bf16 v[108:111], v[146:149], v[196:199], v[108:111]
	v_mfma_f32_16x16x32_bf16 v[76:79], v[154:157], v[196:199], v[76:79]
	v_mfma_f32_16x16x32_bf16 v[104:107], v[146:149], v[204:207], v[104:107]
	v_mfma_f32_16x16x32_bf16 v[72:75], v[154:157], v[204:207], v[72:75]
	v_mfma_f32_16x16x32_bf16 v[100:103], v[146:149], v[212:215], v[100:103]
	v_mfma_f32_16x16x32_bf16 v[68:71], v[154:157], v[212:215], v[68:71]
	v_mfma_f32_16x16x32_bf16 v[96:99], v[146:149], v[220:223], v[96:99]
	v_mfma_f32_16x16x32_bf16 v[64:67], v[154:157], v[220:223], v[64:67]
	v_mfma_f32_16x16x32_bf16 v[108:111], v[150:153], v[200:203], v[108:111]
	v_mfma_f32_16x16x32_bf16 v[76:79], v[158:161], v[200:203], v[76:79]
	v_mfma_f32_16x16x32_bf16 v[104:107], v[150:153], v[208:211], v[104:107]
	v_mfma_f32_16x16x32_bf16 v[72:75], v[158:161], v[208:211], v[72:75]
	v_mfma_f32_16x16x32_bf16 v[100:103], v[150:153], v[216:219], v[100:103]
	v_mfma_f32_16x16x32_bf16 v[68:71], v[158:161], v[216:219], v[68:71]
	v_mfma_f32_16x16x32_bf16 v[96:99], v[150:153], v[224:227], v[96:99]
	v_mfma_f32_16x16x32_bf16 v[64:67], v[158:161], v[224:227], v[64:67]
	s_setprio 0
	s_setprio 1
	v_mfma_f32_16x16x32_bf16 v[44:47], v[180:183], v[196:199], v[44:47]
	v_mfma_f32_16x16x32_bf16 v[12:15], v[188:191], v[196:199], v[12:15]
	v_mfma_f32_16x16x32_bf16 v[40:43], v[180:183], v[204:207], v[40:43]
	v_mfma_f32_16x16x32_bf16 v[8:11], v[188:191], v[204:207], v[8:11]
	v_mfma_f32_16x16x32_bf16 v[36:39], v[180:183], v[212:215], v[36:39]
	v_mfma_f32_16x16x32_bf16 v[4:7], v[188:191], v[212:215], v[4:7]
	v_mfma_f32_16x16x32_bf16 v[32:35], v[180:183], v[220:223], v[32:35]
	v_mfma_f32_16x16x32_bf16 v[0:3], v[188:191], v[220:223], v[0:3]
	v_mfma_f32_16x16x32_bf16 v[44:47], v[184:187], v[200:203], v[44:47]
	v_mfma_f32_16x16x32_bf16 v[12:15], v[192:195], v[200:203], v[12:15]
	v_mfma_f32_16x16x32_bf16 v[40:43], v[184:187], v[208:211], v[40:43]
	v_mfma_f32_16x16x32_bf16 v[8:11], v[192:195], v[208:211], v[8:11]
	v_mfma_f32_16x16x32_bf16 v[36:39], v[184:187], v[216:219], v[36:39]
	v_mfma_f32_16x16x32_bf16 v[4:7], v[192:195], v[216:219], v[4:7]
	v_mfma_f32_16x16x32_bf16 v[32:35], v[184:187], v[224:227], v[32:35]
	v_mfma_f32_16x16x32_bf16 v[0:3], v[192:195], v[224:227], v[0:3]
	s_barrier
; #define PG8_STAGE(bufoff, gbase, voff) do { _Pragma("unroll") for (int _i = 0; _i < 2; ++_i) \
;         __builtin_amdgcn_global_load_lds((const unsigned*)((const char*)(gbase) + (voff)[_i]), (LAS unsigned*)(lds + (bufoff) + ldsw + _i * 8192), 16, 0, 0); } while (0)
; #define PG8_LDA(dst, b, h) do { _Pragma("unroll") for (int m = 0; m < 4; ++m) _Pragma("unroll") for (int k = 0; k < 2; ++k) dst[m][k] = *(const LAS bf16x8*)(lds + PG8_SA(b, h) + aoff + m * 2048 + k * 1024); } while (0)
; #define PG8_LDB(dst, b, h) do { _Pragma("unroll") for (int n = 0; n < 2; ++n) _Pragma("unroll") for (int k = 0; k < 2; ++k) dst[n][k] = *(const LAS bf16x8*)(lds + PG8_SB(b, h) + boff + n * 2048 + k * 1024); } while (0)
; #define PG8_MMA(ai, bj, At, Bt) do { __builtin_amdgcn_s_setprio(1); _Pragma("unroll") for (int m = 0; m < 4; ++m) _Pragma("unroll") for (int n = 0; n < 2; ++n) _Pragma("unroll") for (int k = 0; k < 2; ++k) \
;         acc[ai][bj][m][n] = __builtin_amdgcn_mfma_f32_16x16x32_bf16(Bt[n][k], At[m][k], acc[ai][bj][m][n], 0, 0, 0); __builtin_amdgcn_s_setprio(0); } while (0)
; #define PG8_WAIT_V(n) asm volatile("s_waitcnt vmcnt(" #n ")" ::: "memory")
; #define PG8_WAIT_L(n) asm volatile("s_waitcnt lgkmcnt(" #n ")" ::: "memory")
; #define PG8_BAR __builtin_amdgcn_s_barrier()
; #define PG8_SCHED __builtin_amdgcn_sched_barrier(0)
; template <class Epi, class Sched>
; __device__ __forceinline__ void gemm_phase(LAS unsigned char* lds, const int K, const Sched& S, const Epi& E) {
;     ...
;             PG8_LDB(B0, 1, 0); PG8_LDB(B1, 1, 1); PG8_SCHED; PG8_LDA(At, 1, 0); PG8_STAGE(PG8_SA(0, 1), a2 + hstep, voffA);
;             PG8_WAIT_V(8); PG8_WAIT_L(0); PG8_BAR; PG8_MMA(0, 0, At, B0); PG8_MMA(0, 1, At, B1); PG8_BAR; PG8_SCHED;
;             PG8_LDA(At, 1, 1); PG8_STAGE(PG8_SB(1, 0), b3, voffB); PG8_STAGE(PG8_SB(1, 1), b3 + hstep, voffB); PG8_STAGE(PG8_SA(1, 0), a3, voffA);
;             PG8_WAIT_V(8); PG8_WAIT_L(0); PG8_BAR; PG8_MMA(1, 0, At, B0); PG8_MMA(1, 1, At, B1); PG8_BAR; PG8_SCHED;
;         }
;         if (wr == 0) PG8_BAR;
	s_setprio 0
	s_add_i32 s12, 0, 0x18000
	s_add_i32 s14, 0, 0x1c000
	v_add_u32_e32 v158, s12, v164
	v_add_u32_e32 v167, s14, v164
	ds_read_b128 v[146:149], v158
	ds_read_b128 v[150:153], v158 offset:1024
	ds_read_b128 v[154:157], v158 offset:2048
	ds_read_b128 v[158:161], v158 offset:3072
	ds_read_b128 v[180:183], v167
	ds_read_b128 v[184:187], v167 offset:1024
	ds_read_b128 v[188:191], v167 offset:2048
	ds_read_b128 v[192:195], v167 offset:3072
	s_add_u32 s8, s56, 0xb0000
	s_addc_u32 s9, s57, 0
	s_mov_b32 m0, s64
	ds_read_b128 v[196:199], v166 offset:32768
	ds_read_b128 v[200:203], v166 offset:33792
	ds_read_b128 v[204:207], v166 offset:34816
	ds_read_b128 v[208:211], v166 offset:35840
	ds_read_b128 v[212:215], v166 offset:36864
	ds_read_b128 v[216:219], v166 offset:37888
	ds_read_b128 v[220:223], v166 offset:38912
	ds_read_b128 v[224:227], v166 offset:39936
	global_load_lds_dwordx4 v128, s[8:9]
	s_mov_b32 m0, s65
	s_nop 0
	global_load_lds_dwordx4 v138, s[8:9]
	s_waitcnt vmcnt(8)
	s_waitcnt lgkmcnt(0)
	s_setprio 1
	s_barrier
	v_mfma_f32_16x16x32_bf16 v[124:127], v[146:149], v[196:199], v[124:127]
	v_mfma_f32_16x16x32_bf16 v[92:95], v[154:157], v[196:199], v[92:95]
	v_mfma_f32_16x16x32_bf16 v[120:123], v[146:149], v[204:207], v[120:123]
	v_mfma_f32_16x16x32_bf16 v[88:91], v[154:157], v[204:207], v[88:91]
	v_mfma_f32_16x16x32_bf16 v[116:119], v[146:149], v[212:215], v[116:119]
	v_mfma_f32_16x16x32_bf16 v[84:87], v[154:157], v[212:215], v[84:87]
	v_mfma_f32_16x16x32_bf16 v[112:115], v[146:149], v[220:223], v[112:115]
	v_mfma_f32_16x16x32_bf16 v[80:83], v[154:157], v[220:223], v[80:83]
	v_mfma_f32_16x16x32_bf16 v[124:127], v[150:153], v[200:203], v[124:127]
	v_mfma_f32_16x16x32_bf16 v[92:95], v[158:161], v[200:203], v[92:95]
	v_mfma_f32_16x16x32_bf16 v[120:123], v[150:153], v[208:211], v[120:123]
	v_mfma_f32_16x16x32_bf16 v[88:91], v[158:161], v[208:211], v[88:91]
	v_mfma_f32_16x16x32_bf16 v[116:119], v[150:153], v[216:219], v[116:119]
	v_mfma_f32_16x16x32_bf16 v[84:87], v[158:161], v[216:219], v[84:87]
	v_mfma_f32_16x16x32_bf16 v[112:115], v[150:153], v[224:227], v[112:115]
	v_mfma_f32_16x16x32_bf16 v[80:83], v[158:161], v[224:227], v[80:83]
	s_setprio 0
	s_setprio 1
	v_mfma_f32_16x16x32_bf16 v[60:63], v[180:183], v[196:199], v[60:63]
	v_mfma_f32_16x16x32_bf16 v[28:31], v[188:191], v[196:199], v[28:31]
	v_mfma_f32_16x16x32_bf16 v[56:59], v[180:183], v[204:207], v[56:59]
	v_mfma_f32_16x16x32_bf16 v[24:27], v[188:191], v[204:207], v[24:27]
	v_mfma_f32_16x16x32_bf16 v[52:55], v[180:183], v[212:215], v[52:55]
	v_mfma_f32_16x16x32_bf16 v[20:23], v[188:191], v[212:215], v[20:23]
	v_mfma_f32_16x16x32_bf16 v[48:51], v[180:183], v[220:223], v[48:51]
	v_mfma_f32_16x16x32_bf16 v[16:19], v[188:191], v[220:223], v[16:19]
	v_mfma_f32_16x16x32_bf16 v[60:63], v[184:187], v[200:203], v[60:63]
	v_mfma_f32_16x16x32_bf16 v[28:31], v[192:195], v[200:203], v[28:31]
	v_mfma_f32_16x16x32_bf16 v[56:59], v[184:187], v[208:211], v[56:59]
	v_mfma_f32_16x16x32_bf16 v[24:27], v[192:195], v[208:211], v[24:27]
	v_mfma_f32_16x16x32_bf16 v[52:55], v[184:187], v[216:219], v[52:55]
	v_mfma_f32_16x16x32_bf16 v[20:23], v[192:195], v[216:219], v[20:23]
	v_mfma_f32_16x16x32_bf16 v[48:51], v[184:187], v[224:227], v[48:51]
	v_mfma_f32_16x16x32_bf16 v[16:19], v[192:195], v[224:227], v[16:19]
	s_barrier
	s_setprio 0
	s_add_i32 s8, s12, s60
	s_mov_b32 m0, s8
	ds_read_b128 v[196:199], v166 offset:49152
	ds_read_b128 v[200:203], v166 offset:50176
	ds_read_b128 v[204:207], v166 offset:51200
	ds_read_b128 v[208:211], v166 offset:52224
	ds_read_b128 v[212:215], v166 offset:53248
	ds_read_b128 v[216:219], v166 offset:54272
	ds_read_b128 v[220:223], v166 offset:55296
	ds_read_b128 v[224:227], v166 offset:56320
	s_add_u32 s100, s54, s36
	s_addc_u32 s101, s55, s37
	global_load_lds_dwordx4 v128, s[100:101]
	s_add_i32 m0, s8, 0x2000
	s_add_u32 s8, s54, 0xb0080
	s_addc_u32 s9, s55, 0
	s_add_i32 s12, s14, s60
	s_add_u32 s100, s54, s36
	s_addc_u32 s101, s55, s37
	global_load_lds_dwordx4 v138, s[100:101]
	s_mov_b32 m0, s12
	s_nop 0
	global_load_lds_dwordx4 v128, s[8:9]
	s_add_i32 m0, s12, 0x2000
	s_nop 0
	global_load_lds_dwordx4 v138, s[8:9]
	s_mov_b32 m0, s68
	s_nop 0
	s_add_u32 s100, s56, s36
	s_addc_u32 s101, s57, s37
	global_load_lds_dwordx4 v128, s[100:101]
	s_mov_b32 m0, s69
	s_nop 0
	s_add_u32 s100, s56, s36
	s_addc_u32 s101, s57, s37
	global_load_lds_dwordx4 v138, s[100:101]
	s_waitcnt vmcnt(8)
	s_waitcnt lgkmcnt(0)
	s_setprio 1
	s_barrier
	v_mfma_f32_16x16x32_bf16 v[108:111], v[146:149], v[196:199], v[108:111]
	v_mfma_f32_16x16x32_bf16 v[76:79], v[154:157], v[196:199], v[76:79]
	v_mfma_f32_16x16x32_bf16 v[104:107], v[146:149], v[204:207], v[104:107]
	v_mfma_f32_16x16x32_bf16 v[72:75], v[154:157], v[204:207], v[72:75]
	v_mfma_f32_16x16x32_bf16 v[100:103], v[146:149], v[212:215], v[100:103]
	v_mfma_f32_16x16x32_bf16 v[68:71], v[154:157], v[212:215], v[68:71]
	v_mfma_f32_16x16x32_bf16 v[96:99], v[146:149], v[220:223], v[96:99]
	v_mfma_f32_16x16x32_bf16 v[64:67], v[154:157], v[220:223], v[64:67]
	v_mfma_f32_16x16x32_bf16 v[108:111], v[150:153], v[200:203], v[108:111]
	v_mfma_f32_16x16x32_bf16 v[76:79], v[158:161], v[200:203], v[76:79]
	v_mfma_f32_16x16x32_bf16 v[104:107], v[150:153], v[208:211], v[104:107]
	v_mfma_f32_16x16x32_bf16 v[72:75], v[158:161], v[208:211], v[72:75]
	v_mfma_f32_16x16x32_bf16 v[100:103], v[150:153], v[216:219], v[100:103]
	v_mfma_f32_16x16x32_bf16 v[68:71], v[158:161], v[216:219], v[68:71]
	v_mfma_f32_16x16x32_bf16 v[96:99], v[150:153], v[224:227], v[96:99]
	v_mfma_f32_16x16x32_bf16 v[64:67], v[158:161], v[224:227], v[64:67]
	s_setprio 0
	s_setprio 1
	v_mfma_f32_16x16x32_bf16 v[44:47], v[180:183], v[196:199], v[44:47]
	v_mfma_f32_16x16x32_bf16 v[12:15], v[188:191], v[196:199], v[12:15]
	v_mfma_f32_16x16x32_bf16 v[40:43], v[180:183], v[204:207], v[40:43]
	v_mfma_f32_16x16x32_bf16 v[8:11], v[188:191], v[204:207], v[8:11]
	v_mfma_f32_16x16x32_bf16 v[36:39], v[180:183], v[212:215], v[36:39]
	v_mfma_f32_16x16x32_bf16 v[4:7], v[188:191], v[212:215], v[4:7]
	v_mfma_f32_16x16x32_bf16 v[32:35], v[180:183], v[220:223], v[32:35]
	v_mfma_f32_16x16x32_bf16 v[0:3], v[188:191], v[220:223], v[0:3]
	v_mfma_f32_16x16x32_bf16 v[44:47], v[184:187], v[200:203], v[44:47]
	v_mfma_f32_16x16x32_bf16 v[12:15], v[192:195], v[200:203], v[12:15]
	v_mfma_f32_16x16x32_bf16 v[40:43], v[184:187], v[208:211], v[40:43]
	v_mfma_f32_16x16x32_bf16 v[8:11], v[192:195], v[208:211], v[8:11]
	v_mfma_f32_16x16x32_bf16 v[36:39], v[184:187], v[216:219], v[36:39]
	v_mfma_f32_16x16x32_bf16 v[4:7], v[192:195], v[216:219], v[4:7]
	v_mfma_f32_16x16x32_bf16 v[32:35], v[184:187], v[224:227], v[32:35]
	v_mfma_f32_16x16x32_bf16 v[0:3], v[192:195], v[224:227], v[0:3]
	s_barrier
	s_setprio 0
	s_add_u32 s10, s10, 0x100
	s_addc_u32 s11, s11, 0
	s_cmp_ge_i32 s13, s51
	s_mov_b64 s[8:9], s[52:53]
	s_mov_b32 s12, s13
	s_cbranch_scc0 .LBB0_1073
	s_and_b64 vcc, exec, s[40:41]
	s_cbranch_vccz .LBB0_1076
